# first fragment ds_reads of every tile hoisted above the per-tile scheduling arithmetic (on top of the peeled first K iteration)
# baseline (speedup 1.0000x reference)
; #define PG8_LAS __attribute__((address_space(3)))
; #define PG8_STAGE(bufoff, gbase, voff) do { _Pragma("unroll") for (int _i = 0; _i < 2; ++_i) \
;         __builtin_amdgcn_global_load_lds((const unsigned*)((const char*)(gbase) + (voff)[_i]), (PG8_LAS unsigned*)(lds + (bufoff) + ldsw + _i * 8192), 16, 0, 0); } while (0)
; #define PG8_LDA(dst, b, h) do { _Pragma("unroll") for (int m = 0; m < 4; ++m) _Pragma("unroll") for (int k = 0; k < 2; ++k) dst[m][k] = *(const PG8_LAS bf16x8*)(lds + PG8_SA(b, h) + aoff + m * 2048 + k * 1024); } while (0)
; #define PG8_BAR __builtin_amdgcn_s_barrier()
;     __host__ __device__ bool next(int i, Unit& u) const {
;         const long L = (long)i * G + c; if (L >= nwg) return false;
;         int wgid = (int)L; { const int q = nwg / NXCD, r = nwg % NXCD, xcd = wgid % NXCD, off = wgid / NXCD; wgid = (xcd < r ? xcd * (q + 1) : r * (q + 1) + (xcd - r) * q) + off; }
;         const int nig = wgm * nN, gid = wgid / nig, fm = gid * wgm, gsz = (nM - fm) < wgm ? (nM - fm) : wgm;
;         u.pm = fm + ((wgid % nig) % gsz); u.pn = (wgid % nig) / gsz; return true;
; template <class Epi, class Sched, bool ALIGN_EPI = false, bool SP2 = false, bool ABLK = false, bool BBLK = false>
; __device__ __forceinline__ void gemm_phase(PG8_LAS unsigned char* lds, const Gemm g, const Sched& S, const Epi& E) {
;     ...
;         const bool has_next = S.next(ui + 1, nxt);
;         PG8_LAS unsigned char* const rs_area = lds + STAGE_BYTES + wid * 512;
;         E.stage(cur, rs_area, wr, lane);
;         const char* nA = has_next ? (const char*)g.A + (size_t)nxt.pm * tstep : cA; const char* nB = has_next ? (const char*)g.Bt + (size_t)nxt.pn * tstep : cB;
;         for (int t = 0; t < nt; t += 2) {
;             const bool last = (t == nt - 2);
;             const char* a1 = cA + (size_t)(t + 1) * kstepA;
;             const char* a2 = last ? nA : cA + (size_t)(t + 2) * kstepA; const char* b2 = last ? nB : cB + (size_t)(t + 2) * kstepB;
;             const char* a3 = a2 + kstepA; const char* b3 = b2 + kstepB;
;             if (last && has_next) S.a_ready(nxt);
;             if constexpr (SP2) {
;             PG8_LDB(B0, 0, 0); PG8_LDB(B1, 0, 1); PG8_SCHED; PG8_LDA(At, 0, 0); PG8_STAGE(PG8_SA(1, 1), a1 + hstepA, voffA);
;             PG8_WAIT_V(8); PG8_WAIT_L(0); PG8_BAR; PG8_MMA(0, 0, At, B0); PG8_MMA(0, 1, At, B1); PG8_BAR; PG8_SCHED;
.LBB0_182:
	v_add_u32_e32 v249, 0x10000, v160
	ds_read_b128 v[152:155], v249
	ds_read_b128 v[156:159], v249 offset:1024
	ds_read_b128 v[162:165], v249 offset:2048
	ds_read_b128 v[166:169], v249 offset:3072
	v_add_u32_e32 v249, 0x14000, v160
	ds_read_b128 v[170:173], v249
	ds_read_b128 v[174:177], v249 offset:1024
	ds_read_b128 v[178:181], v249 offset:2048
	ds_read_b128 v[182:185], v249 offset:3072
	ds_read_b128 v[186:189], v161
	ds_read_b128 v[190:193], v161 offset:1024
	ds_read_b128 v[194:197], v161 offset:2048
	ds_read_b128 v[198:201], v161 offset:3072
	ds_read_b128 v[202:205], v161 offset:4096
	ds_read_b128 v[206:209], v161 offset:5120
	ds_read_b128 v[210:213], v161 offset:6144
	ds_read_b128 v[214:217], v161 offset:7168
	s_add_i32 s65, s65, 1
	v_readlane_b32 s2, v253, 16
	v_readlane_b32 s7, v253, 15
	s_mul_i32 s2, s65, s2
	s_mul_hi_u32 s3, s65, s7
	s_add_i32 s3, s3, s2
	s_mul_i32 s2, s65, s7
	s_add_u32 s10, s2, s28
	s_addc_u32 s11, s3, s34
	v_mov_b64_e32 v[4:5], 0x1600
	v_cmp_lt_i64_e64 s[2:3], s[10:11], v[4:5]
	v_mov_b64_e32 v[4:5], 0x15ff
	v_cmp_gt_i64_e32 vcc, s[10:11], v[4:5]
	s_cbranch_vccnz .LBB0_184
	s_ashr_i32 s6, s10, 31
	s_lshr_b32 s6, s6, 29
	s_add_i32 s6, s10, s6
	s_ashr_i32 s7, s6, 3
	s_and_b32 s6, s6, -8
	s_sub_i32 s6, s10, s6
	s_cmp_lt_i32 s6, 0
	s_cselect_b32 s8, s56, 0x2c0
	s_mul_i32 s6, s8, s6
	s_add_i32 s6, s6, s7
	s_mul_hi_i32 s7, s6, 0x2e8ba2e9
	s_lshr_b32 s8, s7, 31
	s_ashr_i32 s7, s7, 5
	s_add_i32 s7, s7, s8
	s_lshl_b32 s8, s7, 2
	s_sub_i32 s9, 0x80, s8
	s_min_i32 s9, s9, 4
	s_abs_i32 s10, s9
	v_cvt_f32_u32_e32 v4, s10
	s_sub_i32 s13, 0, s10
	s_mulk_i32 s7, 0xb0
	s_sub_i32 s7, s6, s7
	v_rcp_iflag_f32_e32 v4, v4
	s_abs_i32 s6, s7
	s_xor_b32 s11, s7, s9
	s_ashr_i32 s11, s11, 31
	v_mul_f32_e32 v4, 0x4f7ffffe, v4
	v_cvt_u32_f32_e32 v4, v4
	s_nop 0
	v_readfirstlane_b32 s16, v4
	s_mul_i32 s13, s13, s16
	s_mul_hi_u32 s13, s16, s13
	s_add_i32 s16, s16, s13
	s_mul_hi_u32 s13, s6, s16
	s_mul_i32 s16, s13, s10
	s_sub_i32 s6, s6, s16
	s_add_i32 s17, s13, 1
	s_sub_i32 s16, s6, s10
	s_cmp_ge_u32 s6, s10
	s_cselect_b32 s13, s17, s13
	s_cselect_b32 s6, s16, s6
	s_add_i32 s16, s13, 1
	s_cmp_ge_u32 s6, s10
	s_cselect_b32 s6, s16, s13
	s_xor_b32 s6, s6, s11
	s_sub_i32 s6, s6, s11
	s_mul_i32 s9, s6, s9
	s_sub_i32 s7, s7, s9
	s_add_i32 s8, s7, s8
.LBB0_184:
	s_lshl_b32 s10, s18, 8
	s_ashr_i32 s11, s10, 31
	s_mov_b32 m0, s64
	v_lshl_add_u64 v[4:5], s[10:11], 2, v[144:145]
	global_load_lds_dword v[4:5], off
	v_lshl_add_u64 v[4:5], v[4:5], 0, s[90:91]
	s_add_i32 m0, s64, 0x100
	s_ashr_i32 s9, s8, 31
	global_load_lds_dword v[4:5], off
	s_lshl_b64 s[10:11], s[8:9], 20
	v_readlane_b32 s16, v252, 27
	v_readlane_b32 s17, v252, 28
	s_add_u32 s10, s16, s10
	s_addc_u32 s11, s17, s11
	s_and_b64 s[16:17], s[2:3], exec
	s_cselect_b32 s9, s11, s21
	s_cselect_b32 s70, s10, s20
	s_ashr_i32 s7, s6, 31
	s_lshl_b64 s[16:17], s[6:7], 20
	s_add_u32 s16, s29, s16
	s_addc_u32 s17, s30, s17
	s_and_b64 s[24:25], s[2:3], exec
	s_cselect_b32 s7, s17, s23
	s_cselect_b32 s71, s16, s22
	s_add_u32 s20, s20, 0xc000
	s_addc_u32 s21, s21, 0
	s_add_u32 s77, s22, 0x10000
	s_addc_u32 vcc_lo, s23, 0
	s_mov_b32 vcc_hi, -2
	s_add_u32 s13, s20, 0x4000
	s_addc_u32 s22, s21, 0
	s_cmp_eq_u32 vcc_hi, 28
	s_cselect_b32 s26, s70, s13
	s_cselect_b32 s27, s9, s22
	s_cselect_b32 s24, s71, s77
	s_cselect_b32 s25, s7, vcc_lo
	s_add_u32 s22, s26, 0x8000
	s_addc_u32 s23, s27, 0
	s_add_i32 s13, 0, 0x10000
	s_add_i32 s88, 0, 0x14000
	s_add_i32 m0, s19, 0xc000
	global_load_lds_dwordx4 v148, s[20:21]
	s_add_i32 m0, s19, 0xe000
	s_nop 0
	global_load_lds_dwordx4 v150, s[20:21]
	s_waitcnt vmcnt(8)
	s_waitcnt lgkmcnt(0)
	v_mfma_f32_16x16x32_bf16 v[132:135], v[152:155], v[186:189], 0
	v_mfma_f32_16x16x32_bf16 v[132:135], v[156:159], v[190:193], v[132:135]
	v_mfma_f32_16x16x32_bf16 v[128:131], v[166:169], v[190:193], 0
	v_mfma_f32_16x16x32_bf16 v[128:131], v[162:165], v[186:189], v[128:131]
	s_barrier
	s_setprio 1
	v_mfma_f32_16x16x32_bf16 v[112:115], v[162:165], v[194:197], 0
	v_mfma_f32_16x16x32_bf16 v[112:115], v[166:169], v[198:201], v[112:115]
	v_mfma_f32_16x16x32_bf16 v[116:119], v[156:159], v[198:201], 0
	v_mfma_f32_16x16x32_bf16 v[116:119], v[152:155], v[194:197], v[116:119]
	v_mfma_f32_16x16x32_bf16 v[100:103], v[152:155], v[202:205], 0
	v_mfma_f32_16x16x32_bf16 v[100:103], v[156:159], v[206:209], v[100:103]
	v_mfma_f32_16x16x32_bf16 v[96:99], v[166:169], v[206:209], 0
	v_mfma_f32_16x16x32_bf16 v[96:99], v[162:165], v[202:205], v[96:99]
	v_mfma_f32_16x16x32_bf16 v[80:83], v[162:165], v[210:213], 0
	v_mfma_f32_16x16x32_bf16 v[80:83], v[166:169], v[214:217], v[80:83]
	v_mfma_f32_16x16x32_bf16 v[84:87], v[156:159], v[214:217], 0
	v_mfma_f32_16x16x32_bf16 v[84:87], v[152:155], v[210:213], v[84:87]
	v_mfma_f32_16x16x32_bf16 v[76:79], v[170:173], v[210:213], 0
	v_mfma_f32_16x16x32_bf16 v[76:79], v[174:177], v[214:217], v[76:79]
	v_mfma_f32_16x16x32_bf16 v[124:127], v[174:177], v[190:193], 0
	v_mfma_f32_16x16x32_bf16 v[124:127], v[170:173], v[186:189], v[124:127]
	v_mfma_f32_16x16x32_bf16 v[120:123], v[178:181], v[186:189], 0
	v_mfma_f32_16x16x32_bf16 v[120:123], v[182:185], v[190:193], v[120:123]
	v_mfma_f32_16x16x32_bf16 v[104:107], v[182:185], v[198:201], 0
	v_mfma_f32_16x16x32_bf16 v[104:107], v[178:181], v[194:197], v[104:107]
	v_mfma_f32_16x16x32_bf16 v[108:111], v[170:173], v[194:197], 0
	v_mfma_f32_16x16x32_bf16 v[108:111], v[174:177], v[198:201], v[108:111]
	v_mfma_f32_16x16x32_bf16 v[92:95], v[174:177], v[206:209], 0
	v_mfma_f32_16x16x32_bf16 v[92:95], v[170:173], v[202:205], v[92:95]
	v_mfma_f32_16x16x32_bf16 v[88:91], v[178:181], v[202:205], 0
	v_mfma_f32_16x16x32_bf16 v[88:91], v[182:185], v[206:209], v[88:91]
	v_mfma_f32_16x16x32_bf16 v[72:75], v[182:185], v[214:217], 0
	v_mfma_f32_16x16x32_bf16 v[72:75], v[178:181], v[210:213], v[72:75]
	s_setprio 0
	s_barrier
; #define PG8_STAGE(bufoff, gbase, voff) do { _Pragma("unroll") for (int _i = 0; _i < 2; ++_i) \
;         __builtin_amdgcn_global_load_lds((const unsigned*)((const char*)(gbase) + (voff)[_i]), (PG8_LAS unsigned*)(lds + (bufoff) + ldsw + _i * 8192), 16, 0, 0); } while (0)
; #define PG8_LDA(dst, b, h) do { _Pragma("unroll") for (int m = 0; m < 4; ++m) _Pragma("unroll") for (int k = 0; k < 2; ++k) dst[m][k] = *(const PG8_LAS bf16x8*)(lds + PG8_SA(b, h) + aoff + m * 2048 + k * 1024); } while (0)
; #define PG8_LDB(dst, b, h) do { _Pragma("unroll") for (int n = 0; n < 2; ++n) _Pragma("unroll") for (int k = 0; k < 2; ++k) dst[n][k] = *(const PG8_LAS bf16x8*)(lds + PG8_SB(b, h) + boff + n * 2048 + k * 1024); } while (0)
; #define PG8_MMA(ai, bj, At, Bt) do { __builtin_amdgcn_s_setprio(1); _Pragma("unroll") for (int m = 0; m < 4; ++m) _Pragma("unroll") for (int n = 0; n < 2; ++n) _Pragma("unroll") for (int k = 0; k < 2; ++k) \
;         acc[ai][bj][m][n] = __builtin_amdgcn_mfma_f32_16x16x32_bf16(Bt[n][k], At[m][k], acc[ai][bj][m][n], 0, 0, 0); __builtin_amdgcn_s_setprio(0); } while (0)
; #define PG8_WAIT_V(n) asm volatile("s_waitcnt vmcnt(" #n ")" ::: "memory")
; #define PG8_WAIT_L(n) asm volatile("s_waitcnt lgkmcnt(" #n ")" ::: "memory")
; #define PG8_BAR __builtin_amdgcn_s_barrier()
; #define PG8_SCHED __builtin_amdgcn_sched_barrier(0)
; template <class Epi, class Sched, bool ALIGN_EPI = false, bool SP2 = false, bool ABLK = false, bool BBLK = false>
; __device__ __forceinline__ void gemm_phase(PG8_LAS unsigned char* lds, const Gemm g, const Sched& S, const Epi& E) {
;     ...
;             PG8_LDA(At, 0, 1); PG8_STAGE(PG8_SB(0, 0), b2, voffB); PG8_STAGE(PG8_SB(0, 1), b2 + hstepB, voffB); PG8_STAGE(PG8_SA(0, 0), a2, voffA);
;             PG8_WAIT_V(8); PG8_WAIT_L(0); PG8_BAR; PG8_MMA(1, 0, At, B0); PG8_MMA(1, 1, At, B1); PG8_BAR; PG8_SCHED;
;             PG8_LDB(B0, 1, 0); PG8_LDB(B1, 1, 1); PG8_SCHED; PG8_LDA(At, 1, 0); PG8_STAGE(PG8_SA(0, 1), a2 + hstepA, voffA);
;             PG8_WAIT_V(8); PG8_WAIT_L(0); PG8_BAR; PG8_MMA(0, 0, At, B0); PG8_MMA(0, 1, At, B1); PG8_BAR; PG8_SCHED;
	s_add_i32 s13, s13, s31
	s_mov_b32 m0, s13
	ds_read_b128 v[186:189], v161 offset:16384
	ds_read_b128 v[190:193], v161 offset:17408
	ds_read_b128 v[194:197], v161 offset:18432
	ds_read_b128 v[198:201], v161 offset:19456
	ds_read_b128 v[202:205], v161 offset:20480
	ds_read_b128 v[206:209], v161 offset:21504
	ds_read_b128 v[210:213], v161 offset:22528
	ds_read_b128 v[214:217], v161 offset:23552
	global_load_lds_dwordx4 v140, s[24:25]
	s_add_i32 m0, s13, 0x2000
	s_add_u32 s68, s24, 0x4000
	s_addc_u32 s69, s25, 0
	s_add_i32 s13, s88, s31
	global_load_lds_dwordx4 v136, s[24:25]
	s_mov_b32 m0, s13
	s_nop 0
	global_load_lds_dwordx4 v140, s[68:69]
	s_add_i32 m0, s13, 0x2000
	s_nop 0
	global_load_lds_dwordx4 v136, s[68:69]
	s_mov_b32 m0, s19
	s_nop 0
	global_load_lds_dwordx4 v142, s[26:27]
	s_mov_b32 m0, s35
	s_nop 0
	global_load_lds_dwordx4 v138, s[26:27]
	s_waitcnt vmcnt(8)
	s_waitcnt lgkmcnt(0)
	v_mfma_f32_16x16x32_bf16 v[68:71], v[152:155], v[186:189], 0
	v_mfma_f32_16x16x32_bf16 v[68:71], v[156:159], v[190:193], v[68:71]
	v_mfma_f32_16x16x32_bf16 v[64:67], v[166:169], v[190:193], 0
	v_mfma_f32_16x16x32_bf16 v[64:67], v[162:165], v[186:189], v[64:67]
	s_barrier
	s_setprio 1
	v_mfma_f32_16x16x32_bf16 v[48:51], v[162:165], v[194:197], 0
	v_mfma_f32_16x16x32_bf16 v[48:51], v[166:169], v[198:201], v[48:51]
	v_mfma_f32_16x16x32_bf16 v[52:55], v[156:159], v[198:201], 0
	v_mfma_f32_16x16x32_bf16 v[52:55], v[152:155], v[194:197], v[52:55]
	v_mfma_f32_16x16x32_bf16 v[32:35], v[152:155], v[202:205], 0
	v_mfma_f32_16x16x32_bf16 v[32:35], v[156:159], v[206:209], v[32:35]
	v_mfma_f32_16x16x32_bf16 v[28:31], v[166:169], v[206:209], 0
	v_mfma_f32_16x16x32_bf16 v[28:31], v[162:165], v[202:205], v[28:31]
	v_mfma_f32_16x16x32_bf16 v[12:15], v[162:165], v[210:213], 0
	v_mfma_f32_16x16x32_bf16 v[12:15], v[166:169], v[214:217], v[12:15]
	v_mfma_f32_16x16x32_bf16 v[16:19], v[156:159], v[214:217], 0
	v_mfma_f32_16x16x32_bf16 v[16:19], v[152:155], v[210:213], v[16:19]
	v_mfma_f32_16x16x32_bf16 v[8:11], v[170:173], v[210:213], 0
	v_mfma_f32_16x16x32_bf16 v[8:11], v[174:177], v[214:217], v[8:11]
	v_mfma_f32_16x16x32_bf16 v[60:63], v[174:177], v[190:193], 0
	v_mfma_f32_16x16x32_bf16 v[60:63], v[170:173], v[186:189], v[60:63]
	v_mfma_f32_16x16x32_bf16 v[56:59], v[178:181], v[186:189], 0
	v_mfma_f32_16x16x32_bf16 v[56:59], v[182:185], v[190:193], v[56:59]
	v_mfma_f32_16x16x32_bf16 v[40:43], v[182:185], v[198:201], 0
	v_mfma_f32_16x16x32_bf16 v[40:43], v[178:181], v[194:197], v[40:43]
	v_mfma_f32_16x16x32_bf16 v[44:47], v[170:173], v[194:197], 0
	v_mfma_f32_16x16x32_bf16 v[44:47], v[174:177], v[198:201], v[44:47]
	v_mfma_f32_16x16x32_bf16 v[24:27], v[174:177], v[206:209], 0
	v_mfma_f32_16x16x32_bf16 v[24:27], v[170:173], v[202:205], v[24:27]
	v_mfma_f32_16x16x32_bf16 v[20:23], v[178:181], v[202:205], 0
	v_mfma_f32_16x16x32_bf16 v[20:23], v[182:185], v[206:209], v[20:23]
	v_mfma_f32_16x16x32_bf16 v[4:7], v[182:185], v[214:217], 0
	v_mfma_f32_16x16x32_bf16 v[4:7], v[178:181], v[210:213], v[4:7]
	s_setprio 0
	s_barrier
	s_add_i32 s13, 0, 0x18000
	v_add_u32_e32 v36, s13, v160
	s_add_i32 s68, 0, 0x1c000
	ds_read_b128 v[152:155], v36
	ds_read_b128 v[156:159], v36 offset:1024
	ds_read_b128 v[162:165], v36 offset:2048
	ds_read_b128 v[166:169], v36 offset:3072
	v_add_u32_e32 v36, s68, v160
	ds_read_b128 v[170:173], v36
	ds_read_b128 v[174:177], v36 offset:1024
	ds_read_b128 v[178:181], v36 offset:2048
	ds_read_b128 v[182:185], v36 offset:3072
	s_add_u32 s26, s26, 0x4000
	s_addc_u32 s27, s27, 0
	s_mov_b32 m0, s36
	ds_read_b128 v[186:189], v161 offset:32768
	ds_read_b128 v[190:193], v161 offset:33792
	ds_read_b128 v[194:197], v161 offset:34816
	ds_read_b128 v[198:201], v161 offset:35840
	ds_read_b128 v[202:205], v161 offset:36864
	ds_read_b128 v[206:209], v161 offset:37888
	ds_read_b128 v[210:213], v161 offset:38912
	ds_read_b128 v[214:217], v161 offset:39936
	global_load_lds_dwordx4 v142, s[26:27]
	s_mov_b32 m0, s37
	s_nop 0
	global_load_lds_dwordx4 v138, s[26:27]
	s_waitcnt vmcnt(8)
	s_waitcnt lgkmcnt(0)
	v_mfma_f32_16x16x32_bf16 v[132:135], v[152:155], v[186:189], v[132:135]
	v_mfma_f32_16x16x32_bf16 v[132:135], v[156:159], v[190:193], v[132:135]
	v_mfma_f32_16x16x32_bf16 v[128:131], v[166:169], v[190:193], v[128:131]
	v_mfma_f32_16x16x32_bf16 v[128:131], v[162:165], v[186:189], v[128:131]
	s_barrier
; #define PG8_STAGE(bufoff, gbase, voff) do { _Pragma("unroll") for (int _i = 0; _i < 2; ++_i) \
;         __builtin_amdgcn_global_load_lds((const unsigned*)((const char*)(gbase) + (voff)[_i]), (PG8_LAS unsigned*)(lds + (bufoff) + ldsw + _i * 8192), 16, 0, 0); } while (0)
; #define PG8_LDA(dst, b, h) do { _Pragma("unroll") for (int m = 0; m < 4; ++m) _Pragma("unroll") for (int k = 0; k < 2; ++k) dst[m][k] = *(const PG8_LAS bf16x8*)(lds + PG8_SA(b, h) + aoff + m * 2048 + k * 1024); } while (0)
; #define PG8_MMA(ai, bj, At, Bt) do { __builtin_amdgcn_s_setprio(1); _Pragma("unroll") for (int m = 0; m < 4; ++m) _Pragma("unroll") for (int n = 0; n < 2; ++n) _Pragma("unroll") for (int k = 0; k < 2; ++k) \
;         acc[ai][bj][m][n] = __builtin_amdgcn_mfma_f32_16x16x32_bf16(Bt[n][k], At[m][k], acc[ai][bj][m][n], 0, 0, 0); __builtin_amdgcn_s_setprio(0); } while (0)
; #define PG8_WAIT_V(n) asm volatile("s_waitcnt vmcnt(" #n ")" ::: "memory")
; #define PG8_WAIT_L(n) asm volatile("s_waitcnt lgkmcnt(" #n ")" ::: "memory")
; #define PG8_BAR __builtin_amdgcn_s_barrier()
; #define PG8_SCHED __builtin_amdgcn_sched_barrier(0)
; template <class Epi, class Sched, bool ALIGN_EPI = false, bool SP2 = false, bool ABLK = false, bool BBLK = false>
; __device__ __forceinline__ void gemm_phase(PG8_LAS unsigned char* lds, const Gemm g, const Sched& S, const Epi& E) {
;     ...
;             PG8_WAIT_V(8); PG8_WAIT_L(0); PG8_BAR; PG8_MMA(0, 0, At, B0); PG8_MMA(0, 1, At, B1); PG8_BAR; PG8_SCHED;
;             PG8_LDA(At, 1, 1); PG8_STAGE(PG8_SB(1, 0), b3, voffB); PG8_STAGE(PG8_SB(1, 1), b3 + hstepB, voffB); PG8_STAGE(PG8_SA(1, 0), a3, voffA);
;             PG8_WAIT_V(8); PG8_WAIT_L(0); PG8_BAR; PG8_MMA(1, 0, At, B0); PG8_MMA(1, 1, At, B1); PG8_BAR; PG8_SCHED;
	s_setprio 1
	v_mfma_f32_16x16x32_bf16 v[112:115], v[162:165], v[194:197], v[112:115]
	v_mfma_f32_16x16x32_bf16 v[112:115], v[166:169], v[198:201], v[112:115]
	v_mfma_f32_16x16x32_bf16 v[116:119], v[156:159], v[198:201], v[116:119]
	v_mfma_f32_16x16x32_bf16 v[116:119], v[152:155], v[194:197], v[116:119]
	v_mfma_f32_16x16x32_bf16 v[100:103], v[152:155], v[202:205], v[100:103]
	v_mfma_f32_16x16x32_bf16 v[100:103], v[156:159], v[206:209], v[100:103]
	v_mfma_f32_16x16x32_bf16 v[96:99], v[166:169], v[206:209], v[96:99]
	v_mfma_f32_16x16x32_bf16 v[96:99], v[162:165], v[202:205], v[96:99]
	v_mfma_f32_16x16x32_bf16 v[80:83], v[162:165], v[210:213], v[80:83]
	v_mfma_f32_16x16x32_bf16 v[80:83], v[166:169], v[214:217], v[80:83]
	v_mfma_f32_16x16x32_bf16 v[84:87], v[156:159], v[214:217], v[84:87]
	v_mfma_f32_16x16x32_bf16 v[84:87], v[152:155], v[210:213], v[84:87]
	v_mfma_f32_16x16x32_bf16 v[76:79], v[170:173], v[210:213], v[76:79]
	v_mfma_f32_16x16x32_bf16 v[76:79], v[174:177], v[214:217], v[76:79]
	v_mfma_f32_16x16x32_bf16 v[124:127], v[174:177], v[190:193], v[124:127]
	v_mfma_f32_16x16x32_bf16 v[124:127], v[170:173], v[186:189], v[124:127]
	v_mfma_f32_16x16x32_bf16 v[120:123], v[178:181], v[186:189], v[120:123]
	v_mfma_f32_16x16x32_bf16 v[120:123], v[182:185], v[190:193], v[120:123]
	v_mfma_f32_16x16x32_bf16 v[104:107], v[182:185], v[198:201], v[104:107]
	v_mfma_f32_16x16x32_bf16 v[104:107], v[178:181], v[194:197], v[104:107]
	v_mfma_f32_16x16x32_bf16 v[108:111], v[170:173], v[194:197], v[108:111]
	v_mfma_f32_16x16x32_bf16 v[108:111], v[174:177], v[198:201], v[108:111]
	v_mfma_f32_16x16x32_bf16 v[92:95], v[174:177], v[206:209], v[92:95]
	v_mfma_f32_16x16x32_bf16 v[92:95], v[170:173], v[202:205], v[92:95]
	v_mfma_f32_16x16x32_bf16 v[88:91], v[178:181], v[202:205], v[88:91]
	v_mfma_f32_16x16x32_bf16 v[88:91], v[182:185], v[206:209], v[88:91]
	v_mfma_f32_16x16x32_bf16 v[72:75], v[182:185], v[214:217], v[72:75]
	v_mfma_f32_16x16x32_bf16 v[72:75], v[178:181], v[210:213], v[72:75]
	s_setprio 0
	s_barrier
	s_add_u32 s26, s24, 0x8000
	s_addc_u32 s27, s25, 0
	s_add_i32 s13, s13, s31
	s_mov_b32 m0, s13
	ds_read_b128 v[186:189], v161 offset:49152
	ds_read_b128 v[190:193], v161 offset:50176
	ds_read_b128 v[194:197], v161 offset:51200
	ds_read_b128 v[198:201], v161 offset:52224
	ds_read_b128 v[202:205], v161 offset:53248
	ds_read_b128 v[206:209], v161 offset:54272
	ds_read_b128 v[210:213], v161 offset:55296
	ds_read_b128 v[214:217], v161 offset:56320
	global_load_lds_dwordx4 v140, s[26:27]
	s_add_i32 m0, s13, 0x2000
	s_add_u32 s24, s24, 0xc000
	s_addc_u32 s25, s25, 0
	s_add_i32 s13, s68, s31
	global_load_lds_dwordx4 v136, s[26:27]
	s_mov_b32 m0, s13
	s_nop 0
	global_load_lds_dwordx4 v140, s[24:25]
	s_add_i32 m0, s13, 0x2000
	s_nop 0
	global_load_lds_dwordx4 v136, s[24:25]
	s_mov_b32 m0, s62
	s_nop 0
	global_load_lds_dwordx4 v142, s[22:23]
	s_mov_b32 m0, s63
	s_nop 0
	global_load_lds_dwordx4 v138, s[22:23]
	s_waitcnt vmcnt(8)
	s_waitcnt lgkmcnt(0)
	v_mfma_f32_16x16x32_bf16 v[68:71], v[152:155], v[186:189], v[68:71]
	v_mfma_f32_16x16x32_bf16 v[68:71], v[156:159], v[190:193], v[68:71]
	v_mfma_f32_16x16x32_bf16 v[64:67], v[166:169], v[190:193], v[64:67]
	v_mfma_f32_16x16x32_bf16 v[64:67], v[162:165], v[186:189], v[64:67]
	s_barrier
	s_setprio 1
	v_mfma_f32_16x16x32_bf16 v[48:51], v[162:165], v[194:197], v[48:51]
	v_mfma_f32_16x16x32_bf16 v[48:51], v[166:169], v[198:201], v[48:51]
	v_mfma_f32_16x16x32_bf16 v[52:55], v[156:159], v[198:201], v[52:55]
	v_mfma_f32_16x16x32_bf16 v[52:55], v[152:155], v[194:197], v[52:55]
	v_mfma_f32_16x16x32_bf16 v[32:35], v[152:155], v[202:205], v[32:35]
	v_mfma_f32_16x16x32_bf16 v[32:35], v[156:159], v[206:209], v[32:35]
	v_mfma_f32_16x16x32_bf16 v[28:31], v[166:169], v[206:209], v[28:31]
	v_mfma_f32_16x16x32_bf16 v[28:31], v[162:165], v[202:205], v[28:31]
	v_mfma_f32_16x16x32_bf16 v[12:15], v[162:165], v[210:213], v[12:15]
	v_mfma_f32_16x16x32_bf16 v[12:15], v[166:169], v[214:217], v[12:15]
	v_mfma_f32_16x16x32_bf16 v[16:19], v[156:159], v[214:217], v[16:19]
	v_mfma_f32_16x16x32_bf16 v[16:19], v[152:155], v[210:213], v[16:19]
	v_mfma_f32_16x16x32_bf16 v[8:11], v[170:173], v[210:213], v[8:11]
	v_mfma_f32_16x16x32_bf16 v[8:11], v[174:177], v[214:217], v[8:11]
	v_mfma_f32_16x16x32_bf16 v[60:63], v[174:177], v[190:193], v[60:63]
	v_mfma_f32_16x16x32_bf16 v[60:63], v[170:173], v[186:189], v[60:63]
	v_mfma_f32_16x16x32_bf16 v[56:59], v[178:181], v[186:189], v[56:59]
	v_mfma_f32_16x16x32_bf16 v[56:59], v[182:185], v[190:193], v[56:59]
	v_mfma_f32_16x16x32_bf16 v[40:43], v[182:185], v[198:201], v[40:43]
	v_mfma_f32_16x16x32_bf16 v[40:43], v[178:181], v[194:197], v[40:43]
	v_mfma_f32_16x16x32_bf16 v[44:47], v[170:173], v[194:197], v[44:47]
	v_mfma_f32_16x16x32_bf16 v[44:47], v[174:177], v[198:201], v[44:47]
	v_mfma_f32_16x16x32_bf16 v[24:27], v[174:177], v[206:209], v[24:27]
	v_mfma_f32_16x16x32_bf16 v[24:27], v[170:173], v[202:205], v[24:27]
	v_mfma_f32_16x16x32_bf16 v[20:23], v[178:181], v[202:205], v[20:23]
	v_mfma_f32_16x16x32_bf16 v[20:23], v[182:185], v[206:209], v[20:23]
	v_mfma_f32_16x16x32_bf16 v[4:7], v[182:185], v[214:217], v[4:7]
	v_mfma_f32_16x16x32_bf16 v[4:7], v[178:181], v[210:213], v[4:7]
	s_setprio 0
	s_barrier
	s_add_i32 vcc_hi, vcc_hi, 2
	s_add_u32 s20, s20, 0x10000
	s_addc_u32 s21, s21, 0
	s_add_u32 s77, s77, 0x10000
	s_addc_u32 vcc_lo, vcc_lo, 0
	s_cmp_gt_u32 vcc_hi, 29

; #define PG8_STAGE(bufoff, gbase, voff) do { _Pragma("unroll") for (int _i = 0; _i < 2; ++_i) \
;         __builtin_amdgcn_global_load_lds((const unsigned*)((const char*)(gbase) + (voff)[_i]), (PG8_LAS unsigned*)(lds + (bufoff) + ldsw + _i * 8192), 16, 0, 0); } while (0)
; #define PG8_LDA(dst, b, h) do { _Pragma("unroll") for (int m = 0; m < 4; ++m) _Pragma("unroll") for (int k = 0; k < 2; ++k) dst[m][k] = *(const PG8_LAS bf16x8*)(lds + PG8_SA(b, h) + aoff + m * 2048 + k * 1024); } while (0)
; #define PG8_LDB(dst, b, h) do { _Pragma("unroll") for (int n = 0; n < 2; ++n) _Pragma("unroll") for (int k = 0; k < 2; ++k) dst[n][k] = *(const PG8_LAS bf16x8*)(lds + PG8_SB(b, h) + boff + n * 2048 + k * 1024); } while (0)
; #define PG8_SCHED __builtin_amdgcn_sched_barrier(0)
;     __host__ __device__ bool next(int i, Unit& u) const {
;         const long L = (long)i * G + c; if (L >= nwg) return false;
;         int wgid = (int)L; { const int q = nwg / NXCD, r = nwg % NXCD, xcd = wgid % NXCD, off = wgid / NXCD; wgid = (xcd < r ? xcd * (q + 1) : r * (q + 1) + (xcd - r) * q) + off; }
; template <class Epi, class Sched, bool ALIGN_EPI = false, bool SP2 = false, bool ABLK = false, bool BBLK = false>
; __device__ __forceinline__ void gemm_phase(PG8_LAS unsigned char* lds, const Gemm g, const Sched& S, const Epi& E) {
;     ...
;             PG8_LDB(B0, 0, 0); PG8_LDB(B1, 0, 1); PG8_SCHED; PG8_LDA(At, 0, 0); PG8_STAGE(PG8_SA(1, 1), a1 + hstepA, voffA);
.LBB0_428:
	v_add_u32_e32 v249, 0x10000, v148
	ds_read_b128 v[152:155], v249
	ds_read_b128 v[156:159], v249 offset:1024
	ds_read_b128 v[160:163], v249 offset:2048
	ds_read_b128 v[164:167], v249 offset:3072
	v_add_u32_e32 v249, 0x14000, v148
	ds_read_b128 v[168:171], v249
	ds_read_b128 v[172:175], v249 offset:1024
	ds_read_b128 v[176:179], v249 offset:2048
	ds_read_b128 v[180:183], v249 offset:3072
	ds_read_b128 v[184:187], v150
	ds_read_b128 v[188:191], v150 offset:1024
	ds_read_b128 v[192:195], v150 offset:2048
	ds_read_b128 v[196:199], v150 offset:3072
	ds_read_b128 v[200:203], v150 offset:4096
	ds_read_b128 v[204:207], v150 offset:5120
	ds_read_b128 v[208:211], v150 offset:6144
	ds_read_b128 v[212:215], v150 offset:7168
	s_add_i32 s82, s82, 1
	s_mul_i32 s0, s82, s34
	s_mul_hi_u32 s1, s82, s31
	s_add_i32 s1, s1, s0
	s_mul_i32 s0, s82, s31
	s_add_u32 s2, s0, s22
	s_addc_u32 s3, s1, s23
	v_cmp_gt_i64_e32 vcc, s[2:3], v[228:229]
	v_cmp_lt_i64_e64 s[0:1], s[2:3], v[250:251]
	s_cbranch_vccnz .LBB0_434
	s_ashr_i32 s3, s2, 31
	s_lshr_b32 s3, s3, 29
	s_add_i32 s8, s2, s3
	s_and_b32 s3, s8, -8
	s_sub_i32 s9, s2, s3
	s_cmp_gt_i32 s9, -1
	s_mov_b64 s[2:3], -1
	s_cbranch_scc0 .LBB0_431
	s_lshl_b32 s12, s9, 7
	s_mov_b64 s[2:3], 0

; #define PG8_STAGE(bufoff, gbase, voff) do { _Pragma("unroll") for (int _i = 0; _i < 2; ++_i) \
;         __builtin_amdgcn_global_load_lds((const unsigned*)((const char*)(gbase) + (voff)[_i]), (PG8_LAS unsigned*)(lds + (bufoff) + ldsw + _i * 8192), 16, 0, 0); } while (0)
; #define PG8_LDA(dst, b, h) do { _Pragma("unroll") for (int m = 0; m < 4; ++m) _Pragma("unroll") for (int k = 0; k < 2; ++k) dst[m][k] = *(const PG8_LAS bf16x8*)(lds + PG8_SA(b, h) + aoff + m * 2048 + k * 1024); } while (0)
; #define PG8_LDB(dst, b, h) do { _Pragma("unroll") for (int n = 0; n < 2; ++n) _Pragma("unroll") for (int k = 0; k < 2; ++k) dst[n][k] = *(const PG8_LAS bf16x8*)(lds + PG8_SB(b, h) + boff + n * 2048 + k * 1024); } while (0)
; #define PG8_WAIT_V(n) asm volatile("s_waitcnt vmcnt(" #n ")" ::: "memory")
; #define PG8_WAIT_L(n) asm volatile("s_waitcnt lgkmcnt(" #n ")" ::: "memory")
; #define PG8_BAR __builtin_amdgcn_s_barrier()
; #define PG8_SCHED __builtin_amdgcn_sched_barrier(0)
; template <class Epi, class Sched, bool ALIGN_EPI = false, bool SP2 = false, bool ABLK = false, bool BBLK = false>
; __device__ __forceinline__ void gemm_phase(PG8_LAS unsigned char* lds, const Gemm g, const Sched& S, const Epi& E) {
;     ...
;         const char* nA = has_next ? (const char*)g.A + (size_t)nxt.pm * tstep : cA; const char* nB = has_next ? (const char*)g.Bt + (size_t)nxt.pn * tstep : cB;
;         for (int t = 0; t < nt; t += 2) {
;             const bool last = (t == nt - 2);
;             const char* a1 = cA + (size_t)(t + 1) * kstepA;
;             const char* a2 = last ? nA : cA + (size_t)(t + 2) * kstepA; const char* b2 = last ? nB : cB + (size_t)(t + 2) * kstepB;
;             const char* a3 = a2 + kstepA; const char* b3 = b2 + kstepB;
;             if (last && has_next) S.a_ready(nxt);
;             if constexpr (SP2) {
;             PG8_LDB(B0, 0, 0); PG8_LDB(B1, 0, 1); PG8_SCHED; PG8_LDA(At, 0, 0); PG8_STAGE(PG8_SA(1, 1), a1 + hstepA, voffA);
;             PG8_WAIT_V(8); PG8_WAIT_L(0); PG8_BAR; PG8_MMA(0, 0, At, B0); PG8_MMA(0, 1, At, B1); PG8_BAR; PG8_SCHED;
;             PG8_LDA(At, 0, 1); PG8_STAGE(PG8_SB(0, 0), b2, voffB); PG8_STAGE(PG8_SB(0, 1), b2 + hstepB, voffB); PG8_STAGE(PG8_SA(0, 0), a2, voffA);
;             PG8_WAIT_V(8); PG8_WAIT_L(0); PG8_BAR; PG8_MMA(1, 0, At, B0); PG8_MMA(1, 1, At, B1); PG8_BAR; PG8_SCHED;
.LBB0_438:
	s_add_u32 s10, s10, 0xc000
	s_addc_u32 s11, s11, 0
	s_add_u32 vcc_lo, s16, 0x10000
	s_addc_u32 vcc_hi, s17, 0
	s_mov_b32 s13, -2
	s_add_u32 s16, s10, 0x4000
	s_addc_u32 s17, s11, 0
	s_cmpk_eq_i32 s13, 0x54
	s_cselect_b32 s20, s0, s16
	s_cselect_b32 s21, s1, s17
	s_cselect_b32 s18, s8, vcc_lo
	s_cselect_b32 s19, s9, vcc_hi
	s_add_u32 s16, s20, 0x8000
	s_addc_u32 s17, s21, 0
	s_add_i32 s68, 0, 0x10000
	s_add_i32 s88, 0, 0x14000
	s_add_i32 m0, s27, 0xc000
	global_load_lds_dwordx4 v144, s[10:11]
	s_add_i32 m0, s27, 0xe000
	s_nop 0
	global_load_lds_dwordx4 v146, s[10:11]
	s_waitcnt vmcnt(8)
	s_waitcnt lgkmcnt(0)
	v_mfma_f32_16x16x32_bf16 v[132:135], v[152:155], v[184:187], 0
	v_mfma_f32_16x16x32_bf16 v[132:135], v[156:159], v[188:191], v[132:135]
	v_mfma_f32_16x16x32_bf16 v[128:131], v[164:167], v[188:191], 0
	v_mfma_f32_16x16x32_bf16 v[128:131], v[160:163], v[184:187], v[128:131]
	s_barrier
	s_setprio 1
	v_mfma_f32_16x16x32_bf16 v[120:123], v[160:163], v[192:195], 0
	v_mfma_f32_16x16x32_bf16 v[120:123], v[164:167], v[196:199], v[120:123]
	v_mfma_f32_16x16x32_bf16 v[124:127], v[156:159], v[196:199], 0
	v_mfma_f32_16x16x32_bf16 v[124:127], v[152:155], v[192:195], v[124:127]
	v_mfma_f32_16x16x32_bf16 v[108:111], v[152:155], v[200:203], 0
	v_mfma_f32_16x16x32_bf16 v[108:111], v[156:159], v[204:207], v[108:111]
	v_mfma_f32_16x16x32_bf16 v[104:107], v[164:167], v[204:207], 0
	v_mfma_f32_16x16x32_bf16 v[104:107], v[160:163], v[200:203], v[104:107]
	v_mfma_f32_16x16x32_bf16 v[88:91], v[160:163], v[208:211], 0
	v_mfma_f32_16x16x32_bf16 v[88:91], v[164:167], v[212:215], v[88:91]
	v_mfma_f32_16x16x32_bf16 v[92:95], v[156:159], v[212:215], 0
	v_mfma_f32_16x16x32_bf16 v[92:95], v[152:155], v[208:211], v[92:95]
	v_mfma_f32_16x16x32_bf16 v[76:79], v[168:171], v[208:211], 0
	v_mfma_f32_16x16x32_bf16 v[76:79], v[172:175], v[212:215], v[76:79]
	v_mfma_f32_16x16x32_bf16 v[116:119], v[172:175], v[188:191], 0
	v_mfma_f32_16x16x32_bf16 v[116:119], v[168:171], v[184:187], v[116:119]
	v_mfma_f32_16x16x32_bf16 v[112:115], v[176:179], v[184:187], 0
	v_mfma_f32_16x16x32_bf16 v[112:115], v[180:183], v[188:191], v[112:115]
	v_mfma_f32_16x16x32_bf16 v[96:99], v[180:183], v[196:199], 0
	v_mfma_f32_16x16x32_bf16 v[96:99], v[176:179], v[192:195], v[96:99]
	v_mfma_f32_16x16x32_bf16 v[100:103], v[168:171], v[192:195], 0
	v_mfma_f32_16x16x32_bf16 v[100:103], v[172:175], v[196:199], v[100:103]
	v_mfma_f32_16x16x32_bf16 v[84:87], v[172:175], v[204:207], 0
	v_mfma_f32_16x16x32_bf16 v[84:87], v[168:171], v[200:203], v[84:87]
	v_mfma_f32_16x16x32_bf16 v[80:83], v[176:179], v[200:203], 0
	v_mfma_f32_16x16x32_bf16 v[80:83], v[180:183], v[204:207], v[80:83]
	v_mfma_f32_16x16x32_bf16 v[72:75], v[180:183], v[212:215], 0
	v_mfma_f32_16x16x32_bf16 v[72:75], v[176:179], v[208:211], v[72:75]
	s_setprio 0
	s_barrier
	s_add_i32 s68, s68, s24
	s_mov_b32 m0, s68
	ds_read_b128 v[184:187], v150 offset:16384
	ds_read_b128 v[188:191], v150 offset:17408
	ds_read_b128 v[192:195], v150 offset:18432
	ds_read_b128 v[196:199], v150 offset:19456
	ds_read_b128 v[200:203], v150 offset:20480
	ds_read_b128 v[204:207], v150 offset:21504
	ds_read_b128 v[208:211], v150 offset:22528
	ds_read_b128 v[212:215], v150 offset:23552
	global_load_lds_dwordx4 v138, s[18:19]
	s_add_i32 m0, s68, 0x2000
	s_add_u32 s68, s18, 0x4000
	s_addc_u32 s69, s19, 0
	s_add_i32 s88, s88, s24
	global_load_lds_dwordx4 v142, s[18:19]
	s_mov_b32 m0, s88
	s_nop 0
	global_load_lds_dwordx4 v138, s[68:69]
	s_add_i32 m0, s88, 0x2000
	s_nop 0
	global_load_lds_dwordx4 v142, s[68:69]
	s_mov_b32 m0, s27
	s_nop 0
	global_load_lds_dwordx4 v136, s[20:21]
	s_mov_b32 m0, s28
	s_nop 0
	global_load_lds_dwordx4 v140, s[20:21]
	s_waitcnt vmcnt(8)
	s_waitcnt lgkmcnt(0)
	v_mfma_f32_16x16x32_bf16 v[68:71], v[152:155], v[184:187], 0
	v_mfma_f32_16x16x32_bf16 v[68:71], v[156:159], v[188:191], v[68:71]
	v_mfma_f32_16x16x32_bf16 v[64:67], v[164:167], v[188:191], 0
	v_mfma_f32_16x16x32_bf16 v[64:67], v[160:163], v[184:187], v[64:67]
	s_barrier
	s_setprio 1
	v_mfma_f32_16x16x32_bf16 v[56:59], v[160:163], v[192:195], 0
	v_mfma_f32_16x16x32_bf16 v[56:59], v[164:167], v[196:199], v[56:59]
	v_mfma_f32_16x16x32_bf16 v[60:63], v[156:159], v[196:199], 0
	v_mfma_f32_16x16x32_bf16 v[60:63], v[152:155], v[192:195], v[60:63]
	v_mfma_f32_16x16x32_bf16 v[44:47], v[152:155], v[200:203], 0
	v_mfma_f32_16x16x32_bf16 v[44:47], v[156:159], v[204:207], v[44:47]
	v_mfma_f32_16x16x32_bf16 v[40:43], v[164:167], v[204:207], 0
	v_mfma_f32_16x16x32_bf16 v[40:43], v[160:163], v[200:203], v[40:43]
	v_mfma_f32_16x16x32_bf16 v[20:23], v[160:163], v[208:211], 0
	v_mfma_f32_16x16x32_bf16 v[20:23], v[164:167], v[212:215], v[20:23]
	v_mfma_f32_16x16x32_bf16 v[24:27], v[156:159], v[212:215], 0
	v_mfma_f32_16x16x32_bf16 v[24:27], v[152:155], v[208:211], v[24:27]
	v_mfma_f32_16x16x32_bf16 v[8:11], v[168:171], v[208:211], 0
	v_mfma_f32_16x16x32_bf16 v[8:11], v[172:175], v[212:215], v[8:11]
	v_mfma_f32_16x16x32_bf16 v[52:55], v[172:175], v[188:191], 0
	v_mfma_f32_16x16x32_bf16 v[52:55], v[168:171], v[184:187], v[52:55]
	v_mfma_f32_16x16x32_bf16 v[48:51], v[176:179], v[184:187], 0
	v_mfma_f32_16x16x32_bf16 v[48:51], v[180:183], v[188:191], v[48:51]
	v_mfma_f32_16x16x32_bf16 v[28:31], v[180:183], v[196:199], 0
	v_mfma_f32_16x16x32_bf16 v[28:31], v[176:179], v[192:195], v[28:31]
	v_mfma_f32_16x16x32_bf16 v[32:35], v[168:171], v[192:195], 0
	v_mfma_f32_16x16x32_bf16 v[32:35], v[172:175], v[196:199], v[32:35]
	v_mfma_f32_16x16x32_bf16 v[16:19], v[172:175], v[204:207], 0
	v_mfma_f32_16x16x32_bf16 v[16:19], v[168:171], v[200:203], v[16:19]
	v_mfma_f32_16x16x32_bf16 v[12:15], v[176:179], v[200:203], 0
	v_mfma_f32_16x16x32_bf16 v[12:15], v[180:183], v[204:207], v[12:15]
	v_mfma_f32_16x16x32_bf16 v[4:7], v[180:183], v[212:215], 0
	v_mfma_f32_16x16x32_bf16 v[4:7], v[176:179], v[208:211], v[4:7]
	s_setprio 0
	s_barrier
; #define PG8_STAGE(bufoff, gbase, voff) do { _Pragma("unroll") for (int _i = 0; _i < 2; ++_i) \
;         __builtin_amdgcn_global_load_lds((const unsigned*)((const char*)(gbase) + (voff)[_i]), (PG8_LAS unsigned*)(lds + (bufoff) + ldsw + _i * 8192), 16, 0, 0); } while (0)
; #define PG8_LDA(dst, b, h) do { _Pragma("unroll") for (int m = 0; m < 4; ++m) _Pragma("unroll") for (int k = 0; k < 2; ++k) dst[m][k] = *(const PG8_LAS bf16x8*)(lds + PG8_SA(b, h) + aoff + m * 2048 + k * 1024); } while (0)
; #define PG8_LDB(dst, b, h) do { _Pragma("unroll") for (int n = 0; n < 2; ++n) _Pragma("unroll") for (int k = 0; k < 2; ++k) dst[n][k] = *(const PG8_LAS bf16x8*)(lds + PG8_SB(b, h) + boff + n * 2048 + k * 1024); } while (0)
; #define PG8_MMA(ai, bj, At, Bt) do { __builtin_amdgcn_s_setprio(1); _Pragma("unroll") for (int m = 0; m < 4; ++m) _Pragma("unroll") for (int n = 0; n < 2; ++n) _Pragma("unroll") for (int k = 0; k < 2; ++k) \
;         acc[ai][bj][m][n] = __builtin_amdgcn_mfma_f32_16x16x32_bf16(Bt[n][k], At[m][k], acc[ai][bj][m][n], 0, 0, 0); __builtin_amdgcn_s_setprio(0); } while (0)
; #define PG8_WAIT_V(n) asm volatile("s_waitcnt vmcnt(" #n ")" ::: "memory")
; #define PG8_WAIT_L(n) asm volatile("s_waitcnt lgkmcnt(" #n ")" ::: "memory")
; #define PG8_BAR __builtin_amdgcn_s_barrier()
; #define PG8_SCHED __builtin_amdgcn_sched_barrier(0)
; template <class Epi, class Sched, bool ALIGN_EPI = false, bool SP2 = false, bool ABLK = false, bool BBLK = false>
; __device__ __forceinline__ void gemm_phase(PG8_LAS unsigned char* lds, const Gemm g, const Sched& S, const Epi& E) {
;     ...
;             PG8_LDB(B0, 1, 0); PG8_LDB(B1, 1, 1); PG8_SCHED; PG8_LDA(At, 1, 0); PG8_STAGE(PG8_SA(0, 1), a2 + hstepA, voffA);
;             PG8_WAIT_V(8); PG8_WAIT_L(0); PG8_BAR; PG8_MMA(0, 0, At, B0); PG8_MMA(0, 1, At, B1); PG8_BAR; PG8_SCHED;
;             PG8_LDA(At, 1, 1); PG8_STAGE(PG8_SB(1, 0), b3, voffB); PG8_STAGE(PG8_SB(1, 1), b3 + hstepB, voffB); PG8_STAGE(PG8_SA(1, 0), a3, voffA);
;             PG8_WAIT_V(8); PG8_WAIT_L(0); PG8_BAR; PG8_MMA(1, 0, At, B0); PG8_MMA(1, 1, At, B1); PG8_BAR; PG8_SCHED;
	s_add_i32 s68, 0, 0x18000
	v_add_u32_e32 v36, s68, v148
	s_add_i32 s69, 0, 0x1c000
	ds_read_b128 v[152:155], v36
	ds_read_b128 v[156:159], v36 offset:1024
	ds_read_b128 v[160:163], v36 offset:2048
	ds_read_b128 v[164:167], v36 offset:3072
	v_add_u32_e32 v36, s69, v148
	ds_read_b128 v[168:171], v36
	ds_read_b128 v[172:175], v36 offset:1024
	ds_read_b128 v[176:179], v36 offset:2048
	ds_read_b128 v[180:183], v36 offset:3072
	s_add_u32 s20, s20, 0x4000
	s_addc_u32 s21, s21, 0
	s_mov_b32 m0, s29
	ds_read_b128 v[184:187], v150 offset:32768
	ds_read_b128 v[188:191], v150 offset:33792
	ds_read_b128 v[192:195], v150 offset:34816
	ds_read_b128 v[196:199], v150 offset:35840
	ds_read_b128 v[200:203], v150 offset:36864
	ds_read_b128 v[204:207], v150 offset:37888
	ds_read_b128 v[208:211], v150 offset:38912
	ds_read_b128 v[212:215], v150 offset:39936
	global_load_lds_dwordx4 v136, s[20:21]
	s_mov_b32 m0, s30
	s_nop 0
	global_load_lds_dwordx4 v140, s[20:21]
	s_waitcnt vmcnt(8)
	s_waitcnt lgkmcnt(0)
	v_mfma_f32_16x16x32_bf16 v[132:135], v[152:155], v[184:187], v[132:135]
	v_mfma_f32_16x16x32_bf16 v[132:135], v[156:159], v[188:191], v[132:135]
	v_mfma_f32_16x16x32_bf16 v[128:131], v[164:167], v[188:191], v[128:131]
	v_mfma_f32_16x16x32_bf16 v[128:131], v[160:163], v[184:187], v[128:131]
	s_barrier
	s_setprio 1
	v_mfma_f32_16x16x32_bf16 v[120:123], v[160:163], v[192:195], v[120:123]
	v_mfma_f32_16x16x32_bf16 v[120:123], v[164:167], v[196:199], v[120:123]
	v_mfma_f32_16x16x32_bf16 v[124:127], v[156:159], v[196:199], v[124:127]
	v_mfma_f32_16x16x32_bf16 v[124:127], v[152:155], v[192:195], v[124:127]
	v_mfma_f32_16x16x32_bf16 v[108:111], v[152:155], v[200:203], v[108:111]
	v_mfma_f32_16x16x32_bf16 v[108:111], v[156:159], v[204:207], v[108:111]
	v_mfma_f32_16x16x32_bf16 v[104:107], v[164:167], v[204:207], v[104:107]
	v_mfma_f32_16x16x32_bf16 v[104:107], v[160:163], v[200:203], v[104:107]
	v_mfma_f32_16x16x32_bf16 v[88:91], v[160:163], v[208:211], v[88:91]
	v_mfma_f32_16x16x32_bf16 v[88:91], v[164:167], v[212:215], v[88:91]
	v_mfma_f32_16x16x32_bf16 v[92:95], v[156:159], v[212:215], v[92:95]
	v_mfma_f32_16x16x32_bf16 v[92:95], v[152:155], v[208:211], v[92:95]
	v_mfma_f32_16x16x32_bf16 v[76:79], v[168:171], v[208:211], v[76:79]
	v_mfma_f32_16x16x32_bf16 v[76:79], v[172:175], v[212:215], v[76:79]
	v_mfma_f32_16x16x32_bf16 v[116:119], v[172:175], v[188:191], v[116:119]
	v_mfma_f32_16x16x32_bf16 v[116:119], v[168:171], v[184:187], v[116:119]
	v_mfma_f32_16x16x32_bf16 v[112:115], v[176:179], v[184:187], v[112:115]
	v_mfma_f32_16x16x32_bf16 v[112:115], v[180:183], v[188:191], v[112:115]
	v_mfma_f32_16x16x32_bf16 v[96:99], v[180:183], v[196:199], v[96:99]
	v_mfma_f32_16x16x32_bf16 v[96:99], v[176:179], v[192:195], v[96:99]
	v_mfma_f32_16x16x32_bf16 v[100:103], v[168:171], v[192:195], v[100:103]
	v_mfma_f32_16x16x32_bf16 v[100:103], v[172:175], v[196:199], v[100:103]
	v_mfma_f32_16x16x32_bf16 v[84:87], v[172:175], v[204:207], v[84:87]
	v_mfma_f32_16x16x32_bf16 v[84:87], v[168:171], v[200:203], v[84:87]
	v_mfma_f32_16x16x32_bf16 v[80:83], v[176:179], v[200:203], v[80:83]
	v_mfma_f32_16x16x32_bf16 v[80:83], v[180:183], v[204:207], v[80:83]
	v_mfma_f32_16x16x32_bf16 v[72:75], v[180:183], v[212:215], v[72:75]
	v_mfma_f32_16x16x32_bf16 v[72:75], v[176:179], v[208:211], v[72:75]
	s_setprio 0
	s_barrier
	s_add_u32 s20, s18, 0x8000
	s_addc_u32 s21, s19, 0
	s_add_i32 s68, s68, s24
	s_mov_b32 m0, s68
	ds_read_b128 v[184:187], v150 offset:49152
	ds_read_b128 v[188:191], v150 offset:50176
	ds_read_b128 v[192:195], v150 offset:51200
	ds_read_b128 v[196:199], v150 offset:52224
	ds_read_b128 v[200:203], v150 offset:53248
	ds_read_b128 v[204:207], v150 offset:54272
	ds_read_b128 v[208:211], v150 offset:55296
	ds_read_b128 v[212:215], v150 offset:56320
	global_load_lds_dwordx4 v138, s[20:21]
	s_add_i32 m0, s68, 0x2000
	s_add_u32 s18, s18, 0xc000
	s_addc_u32 s19, s19, 0
	global_load_lds_dwordx4 v142, s[20:21]
	s_add_i32 s20, s69, s24
	s_mov_b32 m0, s20
	s_nop 0
	global_load_lds_dwordx4 v138, s[18:19]
	s_add_i32 m0, s20, 0x2000
	s_nop 0
	global_load_lds_dwordx4 v142, s[18:19]
	s_mov_b32 m0, s35
	s_nop 0
	global_load_lds_dwordx4 v136, s[16:17]
	s_mov_b32 m0, s70
	s_nop 0
	global_load_lds_dwordx4 v140, s[16:17]
	s_waitcnt vmcnt(8)
	s_waitcnt lgkmcnt(0)
	v_mfma_f32_16x16x32_bf16 v[68:71], v[152:155], v[184:187], v[68:71]
	v_mfma_f32_16x16x32_bf16 v[68:71], v[156:159], v[188:191], v[68:71]
	v_mfma_f32_16x16x32_bf16 v[64:67], v[164:167], v[188:191], v[64:67]
	v_mfma_f32_16x16x32_bf16 v[64:67], v[160:163], v[184:187], v[64:67]
	s_barrier
	s_setprio 1
	v_mfma_f32_16x16x32_bf16 v[56:59], v[160:163], v[192:195], v[56:59]
	v_mfma_f32_16x16x32_bf16 v[56:59], v[164:167], v[196:199], v[56:59]
	v_mfma_f32_16x16x32_bf16 v[60:63], v[156:159], v[196:199], v[60:63]
	v_mfma_f32_16x16x32_bf16 v[60:63], v[152:155], v[192:195], v[60:63]
	v_mfma_f32_16x16x32_bf16 v[44:47], v[152:155], v[200:203], v[44:47]
	v_mfma_f32_16x16x32_bf16 v[44:47], v[156:159], v[204:207], v[44:47]
	v_mfma_f32_16x16x32_bf16 v[40:43], v[164:167], v[204:207], v[40:43]
	v_mfma_f32_16x16x32_bf16 v[40:43], v[160:163], v[200:203], v[40:43]
	v_mfma_f32_16x16x32_bf16 v[20:23], v[160:163], v[208:211], v[20:23]
	v_mfma_f32_16x16x32_bf16 v[20:23], v[164:167], v[212:215], v[20:23]
	v_mfma_f32_16x16x32_bf16 v[24:27], v[156:159], v[212:215], v[24:27]
	v_mfma_f32_16x16x32_bf16 v[24:27], v[152:155], v[208:211], v[24:27]
	v_mfma_f32_16x16x32_bf16 v[8:11], v[168:171], v[208:211], v[8:11]
	v_mfma_f32_16x16x32_bf16 v[8:11], v[172:175], v[212:215], v[8:11]
	v_mfma_f32_16x16x32_bf16 v[52:55], v[172:175], v[188:191], v[52:55]
	v_mfma_f32_16x16x32_bf16 v[52:55], v[168:171], v[184:187], v[52:55]
	v_mfma_f32_16x16x32_bf16 v[48:51], v[176:179], v[184:187], v[48:51]
	v_mfma_f32_16x16x32_bf16 v[48:51], v[180:183], v[188:191], v[48:51]
	v_mfma_f32_16x16x32_bf16 v[28:31], v[180:183], v[196:199], v[28:31]
	v_mfma_f32_16x16x32_bf16 v[28:31], v[176:179], v[192:195], v[28:31]
	v_mfma_f32_16x16x32_bf16 v[32:35], v[168:171], v[192:195], v[32:35]
	v_mfma_f32_16x16x32_bf16 v[32:35], v[172:175], v[196:199], v[32:35]
	v_mfma_f32_16x16x32_bf16 v[16:19], v[172:175], v[204:207], v[16:19]
	v_mfma_f32_16x16x32_bf16 v[16:19], v[168:171], v[200:203], v[16:19]
	v_mfma_f32_16x16x32_bf16 v[12:15], v[176:179], v[200:203], v[12:15]
	v_mfma_f32_16x16x32_bf16 v[12:15], v[180:183], v[204:207], v[12:15]
	v_mfma_f32_16x16x32_bf16 v[4:7], v[180:183], v[212:215], v[4:7]
	v_mfma_f32_16x16x32_bf16 v[4:7], v[176:179], v[208:211], v[4:7]
	s_setprio 0
	s_barrier
	s_add_i32 s13, s13, 2
	s_add_u32 s10, s10, 0x10000
	s_addc_u32 s11, s11, 0
	s_add_u32 vcc_lo, vcc_lo, 0x10000
	s_addc_u32 vcc_hi, vcc_hi, 0
	s_cmpk_gt_u32 s13, 0x55

; #define PG8_STAGE(bufoff, gbase, voff) do { _Pragma("unroll") for (int _i = 0; _i < 2; ++_i) \
;         __builtin_amdgcn_global_load_lds((const unsigned*)((const char*)(gbase) + (voff)[_i]), (PG8_LAS unsigned*)(lds + (bufoff) + ldsw + _i * 8192), 16, 0, 0); } while (0)
; #define PG8_LDA(dst, b, h) do { _Pragma("unroll") for (int m = 0; m < 4; ++m) _Pragma("unroll") for (int k = 0; k < 2; ++k) dst[m][k] = *(const PG8_LAS bf16x8*)(lds + PG8_SA(b, h) + aoff + m * 2048 + k * 1024); } while (0)
; #define PG8_LDB(dst, b, h) do { _Pragma("unroll") for (int n = 0; n < 2; ++n) _Pragma("unroll") for (int k = 0; k < 2; ++k) dst[n][k] = *(const PG8_LAS bf16x8*)(lds + PG8_SB(b, h) + boff + n * 2048 + k * 1024); } while (0)
; #define PG8_SCHED __builtin_amdgcn_sched_barrier(0)
;     __host__ __device__ bool next(int i, Unit& u) const {
;         const long L = (long)i * G + c; if (L >= nwg) return false;
;         int wgid = (int)L; { const int q = nwg / NXCD, r = nwg % NXCD, xcd = wgid % NXCD, off = wgid / NXCD; wgid = (xcd < r ? xcd * (q + 1) : r * (q + 1) + (xcd - r) * q) + off; }
;         const int nig = wgm * nN, gid = wgid / nig, fm = gid * wgm, gsz = (nM - fm) < wgm ? (nM - fm) : wgm;
;         u.pm = fm + ((wgid % nig) % gsz); u.pn = (wgid % nig) / gsz; return true;
; template <class Epi, class Sched, bool ALIGN_EPI = false, bool SP2 = false, bool ABLK = false, bool BBLK = false>
; __device__ __forceinline__ void gemm_phase(PG8_LAS unsigned char* lds, const Gemm g, const Sched& S, const Epi& E) {
;     ...
;             PG8_LDB(B0, 0, 0); PG8_LDB(B1, 0, 1); PG8_SCHED; PG8_LDA(At, 0, 0); PG8_STAGE(PG8_SA(1, 1), a1 + hstepA, voffA);
.LBB0_913:
	v_add_u32_e32 v249, 0x10000, v155
	ds_read_b128 v[150:153], v249
	ds_read_b128 v[158:161], v249 offset:1024
	ds_read_b128 v[162:165], v249 offset:2048
	ds_read_b128 v[166:169], v249 offset:3072
	v_add_u32_e32 v249, 0x14000, v155
	ds_read_b128 v[170:173], v249
	ds_read_b128 v[174:177], v249 offset:1024
	ds_read_b128 v[178:181], v249 offset:2048
	ds_read_b128 v[182:185], v249 offset:3072
	ds_read_b128 v[186:189], v157
	ds_read_b128 v[190:193], v157 offset:1024
	ds_read_b128 v[194:197], v157 offset:2048
	ds_read_b128 v[198:201], v157 offset:3072
	ds_read_b128 v[202:205], v157 offset:4096
	ds_read_b128 v[206:209], v157 offset:5120
	ds_read_b128 v[210:213], v157 offset:6144
	ds_read_b128 v[214:217], v157 offset:7168
	s_add_i32 s64, s64, 1
	v_readlane_b32 s1, v253, 16
	v_readlane_b32 s3, v253, 15
	s_mul_i32 s1, s64, s1
	s_mul_hi_u32 s2, s64, s3
	s_add_i32 s2, s2, s1
	s_mul_i32 s1, s64, s3
	s_add_u32 s10, s1, s28
	s_addc_u32 s11, s2, s30
	v_readlane_b32 s2, v255, 18
	v_readlane_b32 s3, v255, 19
	s_mov_b32 s1, s0
	s_nop 0
	v_mov_b64_e32 v[4:5], s[2:3]
	v_cmp_ge_i64_e32 vcc, s[10:11], v[4:5]
	v_cmp_lt_i64_e64 s[2:3], s[10:11], v[4:5]
	s_cbranch_vccnz .LBB0_915
	s_ashr_i32 s1, s10, 31
	s_lshr_b32 s1, s1, 29
	s_add_i32 s1, s10, s1
	s_ashr_i32 s8, s1, 3
	s_and_b32 s1, s1, -8
	s_sub_i32 s1, s10, s1
	s_lshr_b32 s9, s1, 31
	s_or_b32 s9, s9, s59
	s_mul_i32 s1, s9, s1
	s_add_i32 s1, s1, s8
	s_abs_i32 s9, s1
	s_mul_hi_u32 s10, s9, s61
	s_mul_i32 s11, s10, s60
	s_ashr_i32 s8, s1, 31
	s_sub_i32 s9, s9, s11
	s_xor_b32 s8, s8, s82
	s_add_i32 s11, s10, 1
	s_sub_i32 s13, s9, s60
	s_cmp_ge_u32 s9, s60
	s_cselect_b32 s10, s11, s10
	s_cselect_b32 s9, s13, s9
	s_add_i32 s11, s10, 1
	s_cmp_ge_u32 s9, s60
	s_cselect_b32 s9, s11, s10
	s_xor_b32 s9, s9, s8
	s_sub_i32 s8, s9, s8
	s_lshl_b32 s9, s8, 2
	s_sub_i32 s10, 0x80, s9
	s_min_i32 s10, s10, 4
	s_abs_i32 s11, s10
	v_cvt_f32_u32_e32 v4, s11
	s_sub_i32 s16, 0, s11
	s_mul_i32 s8, s8, s58
	s_sub_i32 s1, s1, s8
	v_rcp_iflag_f32_e32 v4, v4
	s_abs_i32 s13, s1
	s_xor_b32 s8, s1, s10
	s_ashr_i32 s8, s8, 31
	v_mul_f32_e32 v4, 0x4f7ffffe, v4
	v_cvt_u32_f32_e32 v4, v4
	s_nop 0
	v_readfirstlane_b32 s17, v4
	s_mul_i32 s16, s16, s17
	s_mul_hi_u32 s16, s17, s16
	s_add_i32 s17, s17, s16
	s_mul_hi_u32 s16, s13, s17
	s_mul_i32 s17, s16, s11
	s_sub_i32 s13, s13, s17
	s_add_i32 s17, s16, 1
	s_sub_i32 s18, s13, s11
	s_cmp_ge_u32 s13, s11
	s_cselect_b32 s16, s17, s16
	s_cselect_b32 s13, s18, s13
	s_add_i32 s17, s16, 1
	s_cmp_ge_u32 s13, s11
	s_cselect_b32 s11, s17, s16
	s_xor_b32 s11, s11, s8
	s_sub_i32 s8, s11, s8
	s_mul_i32 s10, s8, s10
	s_sub_i32 s1, s1, s10
	s_add_i32 s1, s1, s9
.LBB0_915:
	s_lshl_b32 s18, s0, 8
	s_ashr_i32 s19, s18, 31
	s_mov_b32 m0, s63
	v_lshl_add_u64 v[4:5], s[18:19], 2, v[144:145]
	v_lshl_add_u64 v[6:7], v[4:5], 0, s[90:91]
	global_load_lds_dword v[4:5], off
	s_add_i32 m0, s63, 0x100
	s_mov_b32 s0, s1
	global_load_lds_dword v[6:7], off
	s_ashr_i32 s1, s1, 31
	s_lshl_b64 s[10:11], s[0:1], 20
	v_readlane_b32 s16, v252, 27
	v_readlane_b32 s17, v252, 28
	s_add_u32 s10, s16, s10
	s_addc_u32 s11, s17, s11
	s_and_b64 s[16:17], s[2:3], exec
	s_cselect_b32 s1, s11, s21
	s_cselect_b32 s19, s10, s20
	s_ashr_i32 s9, s8, 31
	s_lshl_b64 s[16:17], s[8:9], 20
	v_readlane_b32 s24, v254, 5
	v_readlane_b32 s25, v254, 6
	s_add_u32 s16, s24, s16
	s_addc_u32 s17, s25, s17
	s_and_b64 s[24:25], s[2:3], exec
	s_cselect_b32 s9, s17, s23
	s_cselect_b32 s65, s16, s22
	s_add_u32 s20, s20, 0xc000
	s_addc_u32 s21, s21, 0
	s_add_u32 s70, s22, 0x10000
	s_addc_u32 s71, s23, 0
	s_mov_b32 s13, -2
	s_add_u32 s22, s20, 0x4000
	s_addc_u32 s23, s21, 0
	s_cmp_eq_u32 s13, 28
	s_cselect_b32 s26, s19, s22
	s_cselect_b32 s27, s1, s23
	s_cselect_b32 s24, s65, s70
	s_cselect_b32 s25, s9, s71
	s_add_u32 s22, s26, 0x8000
	s_addc_u32 s23, s27, 0
	s_add_i32 s68, 0, 0x10000
	s_add_i32 s77, 0, 0x14000
	s_add_i32 m0, s31, 0xc000
	global_load_lds_dwordx4 v146, s[20:21]
	s_add_i32 m0, s31, 0xe000
	s_nop 0
	global_load_lds_dwordx4 v148, s[20:21]
	s_waitcnt vmcnt(8)
	s_waitcnt lgkmcnt(0)
	v_mfma_f32_16x16x32_bf16 v[132:135], v[150:153], v[186:189], 0
	v_mfma_f32_16x16x32_bf16 v[132:135], v[158:161], v[190:193], v[132:135]
	v_mfma_f32_16x16x32_bf16 v[128:131], v[166:169], v[190:193], 0
	v_mfma_f32_16x16x32_bf16 v[128:131], v[162:165], v[186:189], v[128:131]
	s_barrier
	s_setprio 1
	v_mfma_f32_16x16x32_bf16 v[116:119], v[162:165], v[194:197], 0
	v_mfma_f32_16x16x32_bf16 v[116:119], v[166:169], v[198:201], v[116:119]
	v_mfma_f32_16x16x32_bf16 v[124:127], v[158:161], v[198:201], 0
	v_mfma_f32_16x16x32_bf16 v[124:127], v[150:153], v[194:197], v[124:127]
	v_mfma_f32_16x16x32_bf16 v[108:111], v[150:153], v[202:205], 0
	v_mfma_f32_16x16x32_bf16 v[108:111], v[158:161], v[206:209], v[108:111]
	v_mfma_f32_16x16x32_bf16 v[100:103], v[166:169], v[206:209], 0
	v_mfma_f32_16x16x32_bf16 v[100:103], v[162:165], v[202:205], v[100:103]
	v_mfma_f32_16x16x32_bf16 v[84:87], v[162:165], v[210:213], 0
	v_mfma_f32_16x16x32_bf16 v[84:87], v[166:169], v[214:217], v[84:87]
	v_mfma_f32_16x16x32_bf16 v[92:95], v[158:161], v[214:217], 0
	v_mfma_f32_16x16x32_bf16 v[92:95], v[150:153], v[210:213], v[92:95]
	v_mfma_f32_16x16x32_bf16 v[76:79], v[170:173], v[210:213], 0
	v_mfma_f32_16x16x32_bf16 v[76:79], v[174:177], v[214:217], v[76:79]
	v_mfma_f32_16x16x32_bf16 v[120:123], v[174:177], v[190:193], 0
	v_mfma_f32_16x16x32_bf16 v[120:123], v[170:173], v[186:189], v[120:123]
	v_mfma_f32_16x16x32_bf16 v[112:115], v[178:181], v[186:189], 0
	v_mfma_f32_16x16x32_bf16 v[112:115], v[182:185], v[190:193], v[112:115]
	v_mfma_f32_16x16x32_bf16 v[96:99], v[182:185], v[198:201], 0
	v_mfma_f32_16x16x32_bf16 v[96:99], v[178:181], v[194:197], v[96:99]
	v_mfma_f32_16x16x32_bf16 v[104:107], v[170:173], v[194:197], 0
	v_mfma_f32_16x16x32_bf16 v[104:107], v[174:177], v[198:201], v[104:107]
	v_mfma_f32_16x16x32_bf16 v[88:91], v[174:177], v[206:209], 0
	v_mfma_f32_16x16x32_bf16 v[88:91], v[170:173], v[202:205], v[88:91]
	v_mfma_f32_16x16x32_bf16 v[80:83], v[178:181], v[202:205], 0
	v_mfma_f32_16x16x32_bf16 v[80:83], v[182:185], v[206:209], v[80:83]
	v_mfma_f32_16x16x32_bf16 v[72:75], v[182:185], v[214:217], 0
	v_mfma_f32_16x16x32_bf16 v[72:75], v[178:181], v[210:213], v[72:75]
	s_setprio 0
	s_barrier
; #define PG8_STAGE(bufoff, gbase, voff) do { _Pragma("unroll") for (int _i = 0; _i < 2; ++_i) \
;         __builtin_amdgcn_global_load_lds((const unsigned*)((const char*)(gbase) + (voff)[_i]), (PG8_LAS unsigned*)(lds + (bufoff) + ldsw + _i * 8192), 16, 0, 0); } while (0)
; #define PG8_LDA(dst, b, h) do { _Pragma("unroll") for (int m = 0; m < 4; ++m) _Pragma("unroll") for (int k = 0; k < 2; ++k) dst[m][k] = *(const PG8_LAS bf16x8*)(lds + PG8_SA(b, h) + aoff + m * 2048 + k * 1024); } while (0)
; #define PG8_LDB(dst, b, h) do { _Pragma("unroll") for (int n = 0; n < 2; ++n) _Pragma("unroll") for (int k = 0; k < 2; ++k) dst[n][k] = *(const PG8_LAS bf16x8*)(lds + PG8_SB(b, h) + boff + n * 2048 + k * 1024); } while (0)
; #define PG8_MMA(ai, bj, At, Bt) do { __builtin_amdgcn_s_setprio(1); _Pragma("unroll") for (int m = 0; m < 4; ++m) _Pragma("unroll") for (int n = 0; n < 2; ++n) _Pragma("unroll") for (int k = 0; k < 2; ++k) \
;         acc[ai][bj][m][n] = __builtin_amdgcn_mfma_f32_16x16x32_bf16(Bt[n][k], At[m][k], acc[ai][bj][m][n], 0, 0, 0); __builtin_amdgcn_s_setprio(0); } while (0)
; #define PG8_WAIT_V(n) asm volatile("s_waitcnt vmcnt(" #n ")" ::: "memory")
; #define PG8_WAIT_L(n) asm volatile("s_waitcnt lgkmcnt(" #n ")" ::: "memory")
; #define PG8_BAR __builtin_amdgcn_s_barrier()
; #define PG8_SCHED __builtin_amdgcn_sched_barrier(0)
; template <class Epi, class Sched, bool ALIGN_EPI = false, bool SP2 = false, bool ABLK = false, bool BBLK = false>
; __device__ __forceinline__ void gemm_phase(PG8_LAS unsigned char* lds, const Gemm g, const Sched& S, const Epi& E) {
;     ...
;             PG8_LDA(At, 0, 1); PG8_STAGE(PG8_SB(0, 0), b2, voffB); PG8_STAGE(PG8_SB(0, 1), b2 + hstepB, voffB); PG8_STAGE(PG8_SA(0, 0), a2, voffA);
;             PG8_WAIT_V(8); PG8_WAIT_L(0); PG8_BAR; PG8_MMA(1, 0, At, B0); PG8_MMA(1, 1, At, B1); PG8_BAR; PG8_SCHED;
;             PG8_LDB(B0, 1, 0); PG8_LDB(B1, 1, 1); PG8_SCHED; PG8_LDA(At, 1, 0); PG8_STAGE(PG8_SA(0, 1), a2 + hstepA, voffA);
;             PG8_WAIT_V(8); PG8_WAIT_L(0); PG8_BAR; PG8_MMA(0, 0, At, B0); PG8_MMA(0, 1, At, B1); PG8_BAR; PG8_SCHED;
	s_add_i32 s68, s68, s29
	s_mov_b32 m0, s68
	ds_read_b128 v[186:189], v157 offset:16384
	ds_read_b128 v[190:193], v157 offset:17408
	ds_read_b128 v[194:197], v157 offset:18432
	ds_read_b128 v[198:201], v157 offset:19456
	ds_read_b128 v[202:205], v157 offset:20480
	ds_read_b128 v[206:209], v157 offset:21504
	ds_read_b128 v[210:213], v157 offset:22528
	ds_read_b128 v[214:217], v157 offset:23552
	global_load_lds_dwordx4 v140, s[24:25]
	s_add_i32 m0, s68, 0x2000
	s_add_u32 s68, s24, 0x4000
	s_addc_u32 s69, s25, 0
	s_add_i32 s77, s77, s29
	global_load_lds_dwordx4 v136, s[24:25]
	s_mov_b32 m0, s77
	s_nop 0
	global_load_lds_dwordx4 v140, s[68:69]
	s_add_i32 m0, s77, 0x2000
	s_nop 0
	global_load_lds_dwordx4 v136, s[68:69]
	s_mov_b32 m0, s31
	s_nop 0
	global_load_lds_dwordx4 v142, s[26:27]
	s_mov_b32 m0, s34
	s_nop 0
	global_load_lds_dwordx4 v138, s[26:27]
	s_waitcnt vmcnt(8)
	s_waitcnt lgkmcnt(0)
	v_mfma_f32_16x16x32_bf16 v[68:71], v[150:153], v[186:189], 0
	v_mfma_f32_16x16x32_bf16 v[68:71], v[158:161], v[190:193], v[68:71]
	v_mfma_f32_16x16x32_bf16 v[64:67], v[166:169], v[190:193], 0
	v_mfma_f32_16x16x32_bf16 v[64:67], v[162:165], v[186:189], v[64:67]
	s_barrier
	s_setprio 1
	v_mfma_f32_16x16x32_bf16 v[52:55], v[162:165], v[194:197], 0
	v_mfma_f32_16x16x32_bf16 v[52:55], v[166:169], v[198:201], v[52:55]
	v_mfma_f32_16x16x32_bf16 v[60:63], v[158:161], v[198:201], 0
	v_mfma_f32_16x16x32_bf16 v[60:63], v[150:153], v[194:197], v[60:63]
	v_mfma_f32_16x16x32_bf16 v[44:47], v[150:153], v[202:205], 0
	v_mfma_f32_16x16x32_bf16 v[44:47], v[158:161], v[206:209], v[44:47]
	v_mfma_f32_16x16x32_bf16 v[32:35], v[166:169], v[206:209], 0
	v_mfma_f32_16x16x32_bf16 v[32:35], v[162:165], v[202:205], v[32:35]
	v_mfma_f32_16x16x32_bf16 v[16:19], v[162:165], v[210:213], 0
	v_mfma_f32_16x16x32_bf16 v[16:19], v[166:169], v[214:217], v[16:19]
	v_mfma_f32_16x16x32_bf16 v[24:27], v[158:161], v[214:217], 0
	v_mfma_f32_16x16x32_bf16 v[24:27], v[150:153], v[210:213], v[24:27]
	v_mfma_f32_16x16x32_bf16 v[8:11], v[170:173], v[210:213], 0
	v_mfma_f32_16x16x32_bf16 v[8:11], v[174:177], v[214:217], v[8:11]
	v_mfma_f32_16x16x32_bf16 v[56:59], v[174:177], v[190:193], 0
	v_mfma_f32_16x16x32_bf16 v[56:59], v[170:173], v[186:189], v[56:59]
	v_mfma_f32_16x16x32_bf16 v[48:51], v[178:181], v[186:189], 0
	v_mfma_f32_16x16x32_bf16 v[48:51], v[182:185], v[190:193], v[48:51]
	v_mfma_f32_16x16x32_bf16 v[28:31], v[182:185], v[198:201], 0
	v_mfma_f32_16x16x32_bf16 v[28:31], v[178:181], v[194:197], v[28:31]
	v_mfma_f32_16x16x32_bf16 v[40:43], v[170:173], v[194:197], 0
	v_mfma_f32_16x16x32_bf16 v[40:43], v[174:177], v[198:201], v[40:43]
	v_mfma_f32_16x16x32_bf16 v[20:23], v[174:177], v[206:209], 0
	v_mfma_f32_16x16x32_bf16 v[20:23], v[170:173], v[202:205], v[20:23]
	v_mfma_f32_16x16x32_bf16 v[12:15], v[178:181], v[202:205], 0
	v_mfma_f32_16x16x32_bf16 v[12:15], v[182:185], v[206:209], v[12:15]
	v_mfma_f32_16x16x32_bf16 v[4:7], v[182:185], v[214:217], 0
	v_mfma_f32_16x16x32_bf16 v[4:7], v[178:181], v[210:213], v[4:7]
	s_setprio 0
	s_barrier
	s_add_i32 s68, 0, 0x18000
	v_add_u32_e32 v36, s68, v155
	s_add_i32 s69, 0, 0x1c000
	ds_read_b128 v[150:153], v36
	ds_read_b128 v[158:161], v36 offset:1024
	ds_read_b128 v[162:165], v36 offset:2048
	ds_read_b128 v[166:169], v36 offset:3072
	v_add_u32_e32 v36, s69, v155
	ds_read_b128 v[170:173], v36
	ds_read_b128 v[174:177], v36 offset:1024
	ds_read_b128 v[178:181], v36 offset:2048
	ds_read_b128 v[182:185], v36 offset:3072
	s_add_u32 s26, s26, 0x4000
	s_addc_u32 s27, s27, 0
	s_mov_b32 m0, s35
	ds_read_b128 v[186:189], v157 offset:32768
	ds_read_b128 v[190:193], v157 offset:33792
	ds_read_b128 v[194:197], v157 offset:34816
	ds_read_b128 v[198:201], v157 offset:35840
	ds_read_b128 v[202:205], v157 offset:36864
	ds_read_b128 v[206:209], v157 offset:37888
	ds_read_b128 v[210:213], v157 offset:38912
	ds_read_b128 v[214:217], v157 offset:39936
	global_load_lds_dwordx4 v142, s[26:27]
	s_mov_b32 m0, s36
	s_nop 0
	global_load_lds_dwordx4 v138, s[26:27]
	s_waitcnt vmcnt(8)
	s_waitcnt lgkmcnt(0)
	v_mfma_f32_16x16x32_bf16 v[132:135], v[150:153], v[186:189], v[132:135]
	v_mfma_f32_16x16x32_bf16 v[132:135], v[158:161], v[190:193], v[132:135]
	v_mfma_f32_16x16x32_bf16 v[128:131], v[166:169], v[190:193], v[128:131]
	v_mfma_f32_16x16x32_bf16 v[128:131], v[162:165], v[186:189], v[128:131]
	s_barrier
; #define PG8_STAGE(bufoff, gbase, voff) do { _Pragma("unroll") for (int _i = 0; _i < 2; ++_i) \
;         __builtin_amdgcn_global_load_lds((const unsigned*)((const char*)(gbase) + (voff)[_i]), (PG8_LAS unsigned*)(lds + (bufoff) + ldsw + _i * 8192), 16, 0, 0); } while (0)
; #define PG8_LDA(dst, b, h) do { _Pragma("unroll") for (int m = 0; m < 4; ++m) _Pragma("unroll") for (int k = 0; k < 2; ++k) dst[m][k] = *(const PG8_LAS bf16x8*)(lds + PG8_SA(b, h) + aoff + m * 2048 + k * 1024); } while (0)
; #define PG8_MMA(ai, bj, At, Bt) do { __builtin_amdgcn_s_setprio(1); _Pragma("unroll") for (int m = 0; m < 4; ++m) _Pragma("unroll") for (int n = 0; n < 2; ++n) _Pragma("unroll") for (int k = 0; k < 2; ++k) \
;         acc[ai][bj][m][n] = __builtin_amdgcn_mfma_f32_16x16x32_bf16(Bt[n][k], At[m][k], acc[ai][bj][m][n], 0, 0, 0); __builtin_amdgcn_s_setprio(0); } while (0)
; #define PG8_WAIT_V(n) asm volatile("s_waitcnt vmcnt(" #n ")" ::: "memory")
; #define PG8_WAIT_L(n) asm volatile("s_waitcnt lgkmcnt(" #n ")" ::: "memory")
; #define PG8_BAR __builtin_amdgcn_s_barrier()
; #define PG8_SCHED __builtin_amdgcn_sched_barrier(0)
; template <class Epi, class Sched, bool ALIGN_EPI = false, bool SP2 = false, bool ABLK = false, bool BBLK = false>
; __device__ __forceinline__ void gemm_phase(PG8_LAS unsigned char* lds, const Gemm g, const Sched& S, const Epi& E) {
;     ...
;             PG8_WAIT_V(8); PG8_WAIT_L(0); PG8_BAR; PG8_MMA(0, 0, At, B0); PG8_MMA(0, 1, At, B1); PG8_BAR; PG8_SCHED;
;             PG8_LDA(At, 1, 1); PG8_STAGE(PG8_SB(1, 0), b3, voffB); PG8_STAGE(PG8_SB(1, 1), b3 + hstepB, voffB); PG8_STAGE(PG8_SA(1, 0), a3, voffA);
;             PG8_WAIT_V(8); PG8_WAIT_L(0); PG8_BAR; PG8_MMA(1, 0, At, B0); PG8_MMA(1, 1, At, B1); PG8_BAR; PG8_SCHED;
	s_setprio 1
	v_mfma_f32_16x16x32_bf16 v[116:119], v[162:165], v[194:197], v[116:119]
	v_mfma_f32_16x16x32_bf16 v[116:119], v[166:169], v[198:201], v[116:119]
	v_mfma_f32_16x16x32_bf16 v[124:127], v[158:161], v[198:201], v[124:127]
	v_mfma_f32_16x16x32_bf16 v[124:127], v[150:153], v[194:197], v[124:127]
	v_mfma_f32_16x16x32_bf16 v[108:111], v[150:153], v[202:205], v[108:111]
	v_mfma_f32_16x16x32_bf16 v[108:111], v[158:161], v[206:209], v[108:111]
	v_mfma_f32_16x16x32_bf16 v[100:103], v[166:169], v[206:209], v[100:103]
	v_mfma_f32_16x16x32_bf16 v[100:103], v[162:165], v[202:205], v[100:103]
	v_mfma_f32_16x16x32_bf16 v[84:87], v[162:165], v[210:213], v[84:87]
	v_mfma_f32_16x16x32_bf16 v[84:87], v[166:169], v[214:217], v[84:87]
	v_mfma_f32_16x16x32_bf16 v[92:95], v[158:161], v[214:217], v[92:95]
	v_mfma_f32_16x16x32_bf16 v[92:95], v[150:153], v[210:213], v[92:95]
	v_mfma_f32_16x16x32_bf16 v[76:79], v[170:173], v[210:213], v[76:79]
	v_mfma_f32_16x16x32_bf16 v[76:79], v[174:177], v[214:217], v[76:79]
	v_mfma_f32_16x16x32_bf16 v[120:123], v[174:177], v[190:193], v[120:123]
	v_mfma_f32_16x16x32_bf16 v[120:123], v[170:173], v[186:189], v[120:123]
	v_mfma_f32_16x16x32_bf16 v[112:115], v[178:181], v[186:189], v[112:115]
	v_mfma_f32_16x16x32_bf16 v[112:115], v[182:185], v[190:193], v[112:115]
	v_mfma_f32_16x16x32_bf16 v[96:99], v[182:185], v[198:201], v[96:99]
	v_mfma_f32_16x16x32_bf16 v[96:99], v[178:181], v[194:197], v[96:99]
	v_mfma_f32_16x16x32_bf16 v[104:107], v[170:173], v[194:197], v[104:107]
	v_mfma_f32_16x16x32_bf16 v[104:107], v[174:177], v[198:201], v[104:107]
	v_mfma_f32_16x16x32_bf16 v[88:91], v[174:177], v[206:209], v[88:91]
	v_mfma_f32_16x16x32_bf16 v[88:91], v[170:173], v[202:205], v[88:91]
	v_mfma_f32_16x16x32_bf16 v[80:83], v[178:181], v[202:205], v[80:83]
	v_mfma_f32_16x16x32_bf16 v[80:83], v[182:185], v[206:209], v[80:83]
	v_mfma_f32_16x16x32_bf16 v[72:75], v[182:185], v[214:217], v[72:75]
	v_mfma_f32_16x16x32_bf16 v[72:75], v[178:181], v[210:213], v[72:75]
	s_setprio 0
	s_barrier
	s_add_u32 s26, s24, 0x8000
	s_addc_u32 s27, s25, 0
	s_add_i32 s68, s68, s29
	s_mov_b32 m0, s68
	ds_read_b128 v[186:189], v157 offset:49152
	ds_read_b128 v[190:193], v157 offset:50176
	ds_read_b128 v[194:197], v157 offset:51200
	ds_read_b128 v[198:201], v157 offset:52224
	ds_read_b128 v[202:205], v157 offset:53248
	ds_read_b128 v[206:209], v157 offset:54272
	ds_read_b128 v[210:213], v157 offset:55296
	ds_read_b128 v[214:217], v157 offset:56320
	global_load_lds_dwordx4 v140, s[26:27]
	s_add_i32 m0, s68, 0x2000
	s_add_u32 s24, s24, 0xc000
	s_addc_u32 s25, s25, 0
	global_load_lds_dwordx4 v136, s[26:27]
	s_add_i32 s26, s69, s29
	s_mov_b32 m0, s26
	s_nop 0
	global_load_lds_dwordx4 v140, s[24:25]
	s_add_i32 m0, s26, 0x2000
	s_nop 0
	global_load_lds_dwordx4 v136, s[24:25]
	s_mov_b32 m0, s37
	s_nop 0
	global_load_lds_dwordx4 v142, s[22:23]
	s_mov_b32 m0, s62
	s_nop 0
	global_load_lds_dwordx4 v138, s[22:23]
	s_waitcnt vmcnt(8)
	s_waitcnt lgkmcnt(0)
	v_mfma_f32_16x16x32_bf16 v[68:71], v[150:153], v[186:189], v[68:71]
	v_mfma_f32_16x16x32_bf16 v[68:71], v[158:161], v[190:193], v[68:71]
	v_mfma_f32_16x16x32_bf16 v[64:67], v[166:169], v[190:193], v[64:67]
	v_mfma_f32_16x16x32_bf16 v[64:67], v[162:165], v[186:189], v[64:67]
	s_barrier
	s_setprio 1
	v_mfma_f32_16x16x32_bf16 v[52:55], v[162:165], v[194:197], v[52:55]
	v_mfma_f32_16x16x32_bf16 v[52:55], v[166:169], v[198:201], v[52:55]
	v_mfma_f32_16x16x32_bf16 v[60:63], v[158:161], v[198:201], v[60:63]
	v_mfma_f32_16x16x32_bf16 v[60:63], v[150:153], v[194:197], v[60:63]
	v_mfma_f32_16x16x32_bf16 v[44:47], v[150:153], v[202:205], v[44:47]
	v_mfma_f32_16x16x32_bf16 v[44:47], v[158:161], v[206:209], v[44:47]
	v_mfma_f32_16x16x32_bf16 v[32:35], v[166:169], v[206:209], v[32:35]
	v_mfma_f32_16x16x32_bf16 v[32:35], v[162:165], v[202:205], v[32:35]
	v_mfma_f32_16x16x32_bf16 v[16:19], v[162:165], v[210:213], v[16:19]
	v_mfma_f32_16x16x32_bf16 v[16:19], v[166:169], v[214:217], v[16:19]
	v_mfma_f32_16x16x32_bf16 v[24:27], v[158:161], v[214:217], v[24:27]
	v_mfma_f32_16x16x32_bf16 v[24:27], v[150:153], v[210:213], v[24:27]
	v_mfma_f32_16x16x32_bf16 v[8:11], v[170:173], v[210:213], v[8:11]
	v_mfma_f32_16x16x32_bf16 v[8:11], v[174:177], v[214:217], v[8:11]
	v_mfma_f32_16x16x32_bf16 v[56:59], v[174:177], v[190:193], v[56:59]
	v_mfma_f32_16x16x32_bf16 v[56:59], v[170:173], v[186:189], v[56:59]
	v_mfma_f32_16x16x32_bf16 v[48:51], v[178:181], v[186:189], v[48:51]
	v_mfma_f32_16x16x32_bf16 v[48:51], v[182:185], v[190:193], v[48:51]
	v_mfma_f32_16x16x32_bf16 v[28:31], v[182:185], v[198:201], v[28:31]
	v_mfma_f32_16x16x32_bf16 v[28:31], v[178:181], v[194:197], v[28:31]
	v_mfma_f32_16x16x32_bf16 v[40:43], v[170:173], v[194:197], v[40:43]
	v_mfma_f32_16x16x32_bf16 v[40:43], v[174:177], v[198:201], v[40:43]
	v_mfma_f32_16x16x32_bf16 v[20:23], v[174:177], v[206:209], v[20:23]
	v_mfma_f32_16x16x32_bf16 v[20:23], v[170:173], v[202:205], v[20:23]
	v_mfma_f32_16x16x32_bf16 v[12:15], v[178:181], v[202:205], v[12:15]
	v_mfma_f32_16x16x32_bf16 v[12:15], v[182:185], v[206:209], v[12:15]
	v_mfma_f32_16x16x32_bf16 v[4:7], v[182:185], v[214:217], v[4:7]
	v_mfma_f32_16x16x32_bf16 v[4:7], v[178:181], v[210:213], v[4:7]
	s_setprio 0
	s_barrier
	s_add_i32 s13, s13, 2
	s_add_u32 s20, s20, 0x10000
	s_addc_u32 s21, s21, 0
	s_add_u32 s70, s70, 0x10000
	s_addc_u32 s71, s71, 0
	s_cmp_gt_u32 s13, 29

; #define PG8_STAGE(bufoff, gbase, voff) do { _Pragma("unroll") for (int _i = 0; _i < 2; ++_i) \
;         __builtin_amdgcn_global_load_lds((const unsigned*)((const char*)(gbase) + (voff)[_i]), (PG8_LAS unsigned*)(lds + (bufoff) + ldsw + _i * 8192), 16, 0, 0); } while (0)
; #define PG8_LDA(dst, b, h) do { _Pragma("unroll") for (int m = 0; m < 4; ++m) _Pragma("unroll") for (int k = 0; k < 2; ++k) dst[m][k] = *(const PG8_LAS bf16x8*)(lds + PG8_SA(b, h) + aoff + m * 2048 + k * 1024); } while (0)
; #define PG8_LDB(dst, b, h) do { _Pragma("unroll") for (int n = 0; n < 2; ++n) _Pragma("unroll") for (int k = 0; k < 2; ++k) dst[n][k] = *(const PG8_LAS bf16x8*)(lds + PG8_SB(b, h) + boff + n * 2048 + k * 1024); } while (0)
; #define PG8_SCHED __builtin_amdgcn_sched_barrier(0)
;     __host__ __device__ bool next(int i, Unit& u) const {
;         const long L = (long)i * G + c; if (L >= nwg) return false;
;         int wgid = (int)L; { const int q = nwg / NXCD, r = nwg % NXCD, xcd = wgid % NXCD, off = wgid / NXCD; wgid = (xcd < r ? xcd * (q + 1) : r * (q + 1) + (xcd - r) * q) + off; }
; template <class Epi, class Sched, bool ALIGN_EPI = false, bool SP2 = false, bool ABLK = false, bool BBLK = false>
; __device__ __forceinline__ void gemm_phase(PG8_LAS unsigned char* lds, const Gemm g, const Sched& S, const Epi& E) {
;     ...
;             PG8_LDB(B0, 0, 0); PG8_LDB(B1, 0, 1); PG8_SCHED; PG8_LDA(At, 0, 0); PG8_STAGE(PG8_SA(1, 1), a1 + hstepA, voffA);
.LBB0_2104:
	v_add_u32_e32 v249, 0x10000, v148
	ds_read_b128 v[36:39], v249
	ds_read_b128 v[152:155], v249 offset:1024
	ds_read_b128 v[156:159], v249 offset:2048
	ds_read_b128 v[160:163], v249 offset:3072
	v_add_u32_e32 v249, 0x14000, v148
	ds_read_b128 v[164:167], v249
	ds_read_b128 v[168:171], v249 offset:1024
	ds_read_b128 v[172:175], v249 offset:2048
	ds_read_b128 v[176:179], v249 offset:3072
	ds_read_b128 v[180:183], v150
	ds_read_b128 v[184:187], v150 offset:1024
	ds_read_b128 v[188:191], v150 offset:2048
	ds_read_b128 v[192:195], v150 offset:3072
	ds_read_b128 v[196:199], v150 offset:4096
	ds_read_b128 v[200:203], v150 offset:5120
	ds_read_b128 v[204:207], v150 offset:6144
	ds_read_b128 v[208:211], v150 offset:7168
	s_add_i32 s70, s70, 1
	s_mul_i32 s4, s70, s63
	s_mul_hi_u32 s5, s70, s62
	s_add_i32 s5, s5, s4
	s_mul_i32 s4, s70, s62
	s_add_u32 s18, s4, s30
	s_addc_u32 s19, s5, s31
	v_cmp_gt_i64_e32 vcc, s[18:19], v[228:229]
	v_cmp_lt_i64_e64 s[4:5], s[18:19], v[250:251]
	s_cbranch_vccnz .LBB0_2110
	s_ashr_i32 s10, s18, 31
	s_lshr_b32 s10, s10, 29
	s_add_i32 s12, s18, s10
	s_and_b32 s10, s12, -8
	s_sub_i32 s13, s18, s10
	s_cmp_gt_i32 s13, -1
	s_mov_b64 s[10:11], -1
	s_cbranch_scc0 .LBB0_2107
	s_lshl_b32 s16, s13, 7
	s_mov_b64 s[10:11], 0

; #define PG8_LAS __attribute__((address_space(3)))
; #define PG8_STAGE(bufoff, gbase, voff) do { _Pragma("unroll") for (int _i = 0; _i < 2; ++_i) \
;         __builtin_amdgcn_global_load_lds((const unsigned*)((const char*)(gbase) + (voff)[_i]), (PG8_LAS unsigned*)(lds + (bufoff) + ldsw + _i * 8192), 16, 0, 0); } while (0)
; #define PG8_LDA(dst, b, h) do { _Pragma("unroll") for (int m = 0; m < 4; ++m) _Pragma("unroll") for (int k = 0; k < 2; ++k) dst[m][k] = *(const PG8_LAS bf16x8*)(lds + PG8_SA(b, h) + aoff + m * 2048 + k * 1024); } while (0)
; #define PG8_LDB(dst, b, h) do { _Pragma("unroll") for (int n = 0; n < 2; ++n) _Pragma("unroll") for (int k = 0; k < 2; ++k) dst[n][k] = *(const PG8_LAS bf16x8*)(lds + PG8_SB(b, h) + boff + n * 2048 + k * 1024); } while (0)
; #define PG8_WAIT_V(n) asm volatile("s_waitcnt vmcnt(" #n ")" ::: "memory")
; template <class Epi, class Sched, bool ALIGN_EPI = false, bool SP2 = false, bool ABLK = false, bool BBLK = false>
; __device__ __forceinline__ void gemm_phase(PG8_LAS unsigned char* lds, const Gemm g, const Sched& S, const Epi& E) {
;     ...
;         const bool has_next = S.next(ui + 1, nxt);
;         PG8_LAS unsigned char* const rs_area = lds + STAGE_BYTES + wid * 512;
;         E.stage(cur, rs_area, wr, lane);
;         const char* nA = has_next ? (const char*)g.A + (size_t)nxt.pm * tstep : cA; const char* nB = has_next ? (const char*)g.Bt + (size_t)nxt.pn * tstep : cB;
;         for (int t = 0; t < nt; t += 2) {
;             const bool last = (t == nt - 2);
;             const char* a1 = cA + (size_t)(t + 1) * kstepA;
;             const char* a2 = last ? nA : cA + (size_t)(t + 2) * kstepA; const char* b2 = last ? nB : cB + (size_t)(t + 2) * kstepB;
;             const char* a3 = a2 + kstepA; const char* b3 = b2 + kstepB;
;             if (last && has_next) S.a_ready(nxt);
;             if constexpr (SP2) {
;             PG8_LDB(B0, 0, 0); PG8_LDB(B1, 0, 1); PG8_SCHED; PG8_LDA(At, 0, 0); PG8_STAGE(PG8_SA(1, 1), a1 + hstepA, voffA);
;             PG8_WAIT_V(8); PG8_WAIT_L(0); PG8_BAR; PG8_MMA(0, 0, At, B0); PG8_MMA(0, 1, At, B1); PG8_BAR; PG8_SCHED;
;             PG8_LDA(At, 0, 1); PG8_STAGE(PG8_SB(0, 0), b2, voffB); PG8_STAGE(PG8_SB(0, 1), b2 + hstepB, voffB); PG8_STAGE(PG8_SA(0, 0), a2, voffA);
;             PG8_WAIT_V(8); PG8_WAIT_L(0); PG8_BAR; PG8_MMA(1, 0, At, B0); PG8_MMA(1, 1, At, B1); PG8_BAR; PG8_SCHED;
.LBB0_2110:
	s_ashr_i32 s17, s16, 31
	s_lshl_b64 s[12:13], s[16:17], 20
	s_add_u32 s18, s72, s12
	s_addc_u32 s19, s73, s13
	s_and_b64 s[12:13], s[4:5], exec
	s_cselect_b32 s12, s19, s23
	s_cselect_b32 s17, s18, s22
	s_ashr_i32 s11, s10, 31
	s_lshl_b64 s[20:21], s[10:11], 20
	v_readlane_b32 s26, v254, 3
	v_readlane_b32 s27, v254, 4
	s_add_u32 s20, s26, s20
	s_addc_u32 s21, s27, s21
	s_and_b64 s[26:27], s[4:5], exec
	s_cselect_b32 s11, s21, s25
	s_cselect_b32 s77, s20, s24
	s_add_u32 s22, s22, 0xc000
	s_addc_u32 s23, s23, 0
	s_add_u32 s82, s24, 0x10000
	s_addc_u32 vcc_lo, s25, 0
	s_mov_b32 s13, -2
	s_add_u32 s24, s22, 0x4000
	s_addc_u32 s25, s23, 0
	s_cmp_eq_u32 s13, 28
	s_cselect_b32 s28, s17, s24
	s_cselect_b32 s29, s12, s25
	s_cselect_b32 s26, s77, s82
	s_cselect_b32 s27, s11, vcc_lo
	s_add_u32 s24, s28, 0x8000
	s_addc_u32 s25, s29, 0
	s_add_i32 s68, 0, 0x10000
	s_add_i32 s88, 0, 0x14000
	s_add_i32 m0, s9, 0xc000
	global_load_lds_dwordx4 v144, s[22:23]
	s_add_i32 m0, s9, 0xe000
	s_nop 0
	global_load_lds_dwordx4 v146, s[22:23]
	s_waitcnt vmcnt(8)
	s_waitcnt lgkmcnt(0)
	v_mfma_f32_16x16x32_bf16 v[132:135], v[36:39], v[180:183], 0
	v_mfma_f32_16x16x32_bf16 v[132:135], v[152:155], v[184:187], v[132:135]
	v_mfma_f32_16x16x32_bf16 v[128:131], v[160:163], v[184:187], 0
	v_mfma_f32_16x16x32_bf16 v[128:131], v[156:159], v[180:183], v[128:131]
	s_barrier
	s_setprio 1
	v_mfma_f32_16x16x32_bf16 v[120:123], v[156:159], v[188:191], 0
	v_mfma_f32_16x16x32_bf16 v[120:123], v[160:163], v[192:195], v[120:123]
	v_mfma_f32_16x16x32_bf16 v[124:127], v[152:155], v[192:195], 0
	v_mfma_f32_16x16x32_bf16 v[124:127], v[36:39], v[188:191], v[124:127]
	v_mfma_f32_16x16x32_bf16 v[108:111], v[36:39], v[196:199], 0
	v_mfma_f32_16x16x32_bf16 v[108:111], v[152:155], v[200:203], v[108:111]
	v_mfma_f32_16x16x32_bf16 v[104:107], v[160:163], v[200:203], 0
	v_mfma_f32_16x16x32_bf16 v[104:107], v[156:159], v[196:199], v[104:107]
	v_mfma_f32_16x16x32_bf16 v[88:91], v[156:159], v[204:207], 0
	v_mfma_f32_16x16x32_bf16 v[88:91], v[160:163], v[208:211], v[88:91]
	v_mfma_f32_16x16x32_bf16 v[92:95], v[152:155], v[208:211], 0
	v_mfma_f32_16x16x32_bf16 v[92:95], v[36:39], v[204:207], v[92:95]
	v_mfma_f32_16x16x32_bf16 v[76:79], v[164:167], v[204:207], 0
	v_mfma_f32_16x16x32_bf16 v[76:79], v[168:171], v[208:211], v[76:79]
	v_mfma_f32_16x16x32_bf16 v[116:119], v[168:171], v[184:187], 0
	v_mfma_f32_16x16x32_bf16 v[116:119], v[164:167], v[180:183], v[116:119]
	v_mfma_f32_16x16x32_bf16 v[112:115], v[172:175], v[180:183], 0
	v_mfma_f32_16x16x32_bf16 v[112:115], v[176:179], v[184:187], v[112:115]
	v_mfma_f32_16x16x32_bf16 v[96:99], v[176:179], v[192:195], 0
	v_mfma_f32_16x16x32_bf16 v[96:99], v[172:175], v[188:191], v[96:99]
	v_mfma_f32_16x16x32_bf16 v[100:103], v[164:167], v[188:191], 0
	v_mfma_f32_16x16x32_bf16 v[100:103], v[168:171], v[192:195], v[100:103]
	v_mfma_f32_16x16x32_bf16 v[84:87], v[168:171], v[200:203], 0
	v_mfma_f32_16x16x32_bf16 v[84:87], v[164:167], v[196:199], v[84:87]
	v_mfma_f32_16x16x32_bf16 v[80:83], v[172:175], v[196:199], 0
	v_mfma_f32_16x16x32_bf16 v[80:83], v[176:179], v[200:203], v[80:83]
	v_mfma_f32_16x16x32_bf16 v[72:75], v[176:179], v[208:211], 0
	v_mfma_f32_16x16x32_bf16 v[72:75], v[172:175], v[204:207], v[72:75]
	s_setprio 0
	s_barrier
	s_add_i32 s68, s68, s34
	s_mov_b32 m0, s68
	ds_read_b128 v[180:183], v150 offset:16384
	ds_read_b128 v[184:187], v150 offset:17408
	ds_read_b128 v[188:191], v150 offset:18432
	ds_read_b128 v[192:195], v150 offset:19456
	ds_read_b128 v[196:199], v150 offset:20480
	ds_read_b128 v[200:203], v150 offset:21504
	ds_read_b128 v[204:207], v150 offset:22528
	ds_read_b128 v[208:211], v150 offset:23552
	global_load_lds_dwordx4 v138, s[26:27]
	s_add_i32 m0, s68, 0x2000
	s_add_u32 s68, s26, 0x4000
	s_addc_u32 s69, s27, 0
	s_add_i32 s88, s88, s34
	global_load_lds_dwordx4 v142, s[26:27]
	s_mov_b32 m0, s88
	s_nop 0
	global_load_lds_dwordx4 v138, s[68:69]
	s_add_i32 m0, s88, 0x2000
	s_nop 0
	global_load_lds_dwordx4 v142, s[68:69]
	s_mov_b32 m0, s9
	s_nop 0
	global_load_lds_dwordx4 v136, s[28:29]
	s_mov_b32 m0, s35
	s_nop 0
	global_load_lds_dwordx4 v140, s[28:29]
	s_waitcnt vmcnt(8)
	s_waitcnt lgkmcnt(0)
	v_mfma_f32_16x16x32_bf16 v[68:71], v[36:39], v[180:183], 0
	v_mfma_f32_16x16x32_bf16 v[68:71], v[152:155], v[184:187], v[68:71]
	v_mfma_f32_16x16x32_bf16 v[64:67], v[160:163], v[184:187], 0
	v_mfma_f32_16x16x32_bf16 v[64:67], v[156:159], v[180:183], v[64:67]
	s_barrier
	s_setprio 1
	v_mfma_f32_16x16x32_bf16 v[56:59], v[156:159], v[188:191], 0
	v_mfma_f32_16x16x32_bf16 v[56:59], v[160:163], v[192:195], v[56:59]
	v_mfma_f32_16x16x32_bf16 v[60:63], v[152:155], v[192:195], 0
	v_mfma_f32_16x16x32_bf16 v[60:63], v[36:39], v[188:191], v[60:63]
	v_mfma_f32_16x16x32_bf16 v[44:47], v[36:39], v[196:199], 0
	v_mfma_f32_16x16x32_bf16 v[44:47], v[152:155], v[200:203], v[44:47]
	v_mfma_f32_16x16x32_bf16 v[40:43], v[160:163], v[200:203], 0
	v_mfma_f32_16x16x32_bf16 v[40:43], v[156:159], v[196:199], v[40:43]
	v_mfma_f32_16x16x32_bf16 v[20:23], v[156:159], v[204:207], 0
	v_mfma_f32_16x16x32_bf16 v[20:23], v[160:163], v[208:211], v[20:23]
	v_mfma_f32_16x16x32_bf16 v[24:27], v[152:155], v[208:211], 0
	v_mfma_f32_16x16x32_bf16 v[24:27], v[36:39], v[204:207], v[24:27]
	v_mfma_f32_16x16x32_bf16 v[48:51], v[172:175], v[180:183], 0
	v_mfma_f32_16x16x32_bf16 v[32:35], v[164:167], v[188:191], 0
	v_mfma_f32_16x16x32_bf16 v[28:31], v[172:175], v[188:191], 0
	v_mfma_f32_16x16x32_bf16 v[16:19], v[164:167], v[196:199], 0
	v_mfma_f32_16x16x32_bf16 v[12:15], v[172:175], v[196:199], 0
	v_mfma_f32_16x16x32_bf16 v[8:11], v[164:167], v[204:207], 0
	v_mfma_f32_16x16x32_bf16 v[4:7], v[172:175], v[204:207], 0
	v_mfma_f32_16x16x32_bf16 v[36:39], v[164:167], v[180:183], 0
	v_mfma_f32_16x16x32_bf16 v[48:51], v[176:179], v[184:187], v[48:51]
	v_mfma_f32_16x16x32_bf16 v[32:35], v[168:171], v[192:195], v[32:35]
	v_mfma_f32_16x16x32_bf16 v[28:31], v[176:179], v[192:195], v[28:31]
	v_mfma_f32_16x16x32_bf16 v[16:19], v[168:171], v[200:203], v[16:19]
	v_mfma_f32_16x16x32_bf16 v[12:15], v[176:179], v[200:203], v[12:15]
	v_mfma_f32_16x16x32_bf16 v[8:11], v[168:171], v[208:211], v[8:11]
	v_mfma_f32_16x16x32_bf16 v[4:7], v[176:179], v[208:211], v[4:7]
	v_mfma_f32_16x16x32_bf16 v[36:39], v[168:171], v[184:187], v[36:39]
	s_setprio 0
	s_barrier
; #define PG8_STAGE(bufoff, gbase, voff) do { _Pragma("unroll") for (int _i = 0; _i < 2; ++_i) \
;         __builtin_amdgcn_global_load_lds((const unsigned*)((const char*)(gbase) + (voff)[_i]), (PG8_LAS unsigned*)(lds + (bufoff) + ldsw + _i * 8192), 16, 0, 0); } while (0)
; #define PG8_LDA(dst, b, h) do { _Pragma("unroll") for (int m = 0; m < 4; ++m) _Pragma("unroll") for (int k = 0; k < 2; ++k) dst[m][k] = *(const PG8_LAS bf16x8*)(lds + PG8_SA(b, h) + aoff + m * 2048 + k * 1024); } while (0)
; #define PG8_LDB(dst, b, h) do { _Pragma("unroll") for (int n = 0; n < 2; ++n) _Pragma("unroll") for (int k = 0; k < 2; ++k) dst[n][k] = *(const PG8_LAS bf16x8*)(lds + PG8_SB(b, h) + boff + n * 2048 + k * 1024); } while (0)
; #define PG8_MMA(ai, bj, At, Bt) do { __builtin_amdgcn_s_setprio(1); _Pragma("unroll") for (int m = 0; m < 4; ++m) _Pragma("unroll") for (int n = 0; n < 2; ++n) _Pragma("unroll") for (int k = 0; k < 2; ++k) \
;         acc[ai][bj][m][n] = __builtin_amdgcn_mfma_f32_16x16x32_bf16(Bt[n][k], At[m][k], acc[ai][bj][m][n], 0, 0, 0); __builtin_amdgcn_s_setprio(0); } while (0)
; #define PG8_WAIT_V(n) asm volatile("s_waitcnt vmcnt(" #n ")" ::: "memory")
; #define PG8_WAIT_L(n) asm volatile("s_waitcnt lgkmcnt(" #n ")" ::: "memory")
; #define PG8_BAR __builtin_amdgcn_s_barrier()
; #define PG8_SCHED __builtin_amdgcn_sched_barrier(0)
; template <class Epi, class Sched, bool ALIGN_EPI = false, bool SP2 = false, bool ABLK = false, bool BBLK = false>
; __device__ __forceinline__ void gemm_phase(PG8_LAS unsigned char* lds, const Gemm g, const Sched& S, const Epi& E) {
;     ...
;             PG8_LDB(B0, 1, 0); PG8_LDB(B1, 1, 1); PG8_SCHED; PG8_LDA(At, 1, 0); PG8_STAGE(PG8_SA(0, 1), a2 + hstepA, voffA);
;             PG8_WAIT_V(8); PG8_WAIT_L(0); PG8_BAR; PG8_MMA(0, 0, At, B0); PG8_MMA(0, 1, At, B1); PG8_BAR; PG8_SCHED;
;             PG8_LDA(At, 1, 1); PG8_STAGE(PG8_SB(1, 0), b3, voffB); PG8_STAGE(PG8_SB(1, 1), b3 + hstepB, voffB); PG8_STAGE(PG8_SA(1, 0), a3, voffA);
;             PG8_WAIT_V(8); PG8_WAIT_L(0); PG8_BAR; PG8_MMA(1, 0, At, B0); PG8_MMA(1, 1, At, B1); PG8_BAR; PG8_SCHED;
	s_add_i32 s68, 0, 0x18000
	v_add_u32_e32 v151, s68, v148
	s_add_i32 s69, 0, 0x1c000
	ds_read_b128 v[52:55], v151
	ds_read_b128 v[152:155], v151 offset:1024
	ds_read_b128 v[156:159], v151 offset:2048
	ds_read_b128 v[160:163], v151 offset:3072
	v_add_u32_e32 v151, s69, v148
	ds_read_b128 v[164:167], v151
	ds_read_b128 v[168:171], v151 offset:1024
	ds_read_b128 v[172:175], v151 offset:2048
	ds_read_b128 v[176:179], v151 offset:3072
	s_add_u32 s28, s28, 0x4000
	s_addc_u32 s29, s29, 0
	s_mov_b32 m0, s36
	ds_read_b128 v[180:183], v150 offset:32768
	ds_read_b128 v[184:187], v150 offset:33792
	ds_read_b128 v[188:191], v150 offset:34816
	ds_read_b128 v[192:195], v150 offset:35840
	ds_read_b128 v[196:199], v150 offset:36864
	ds_read_b128 v[200:203], v150 offset:37888
	ds_read_b128 v[204:207], v150 offset:38912
	ds_read_b128 v[208:211], v150 offset:39936
	global_load_lds_dwordx4 v136, s[28:29]
	s_mov_b32 m0, s37
	s_nop 0
	global_load_lds_dwordx4 v140, s[28:29]
	s_waitcnt vmcnt(8)
	s_waitcnt lgkmcnt(0)
	v_mfma_f32_16x16x32_bf16 v[132:135], v[52:55], v[180:183], v[132:135]
	v_mfma_f32_16x16x32_bf16 v[132:135], v[152:155], v[184:187], v[132:135]
	v_mfma_f32_16x16x32_bf16 v[128:131], v[160:163], v[184:187], v[128:131]
	v_mfma_f32_16x16x32_bf16 v[128:131], v[156:159], v[180:183], v[128:131]
	s_barrier
	s_setprio 1
	v_mfma_f32_16x16x32_bf16 v[120:123], v[156:159], v[188:191], v[120:123]
	v_mfma_f32_16x16x32_bf16 v[120:123], v[160:163], v[192:195], v[120:123]
	v_mfma_f32_16x16x32_bf16 v[124:127], v[152:155], v[192:195], v[124:127]
	v_mfma_f32_16x16x32_bf16 v[124:127], v[52:55], v[188:191], v[124:127]
	v_mfma_f32_16x16x32_bf16 v[108:111], v[52:55], v[196:199], v[108:111]
	v_mfma_f32_16x16x32_bf16 v[108:111], v[152:155], v[200:203], v[108:111]
	v_mfma_f32_16x16x32_bf16 v[104:107], v[160:163], v[200:203], v[104:107]
	v_mfma_f32_16x16x32_bf16 v[104:107], v[156:159], v[196:199], v[104:107]
	v_mfma_f32_16x16x32_bf16 v[88:91], v[156:159], v[204:207], v[88:91]
	v_mfma_f32_16x16x32_bf16 v[88:91], v[160:163], v[208:211], v[88:91]
	v_mfma_f32_16x16x32_bf16 v[92:95], v[152:155], v[208:211], v[92:95]
	v_mfma_f32_16x16x32_bf16 v[92:95], v[52:55], v[204:207], v[92:95]
	v_mfma_f32_16x16x32_bf16 v[76:79], v[164:167], v[204:207], v[76:79]
	v_mfma_f32_16x16x32_bf16 v[76:79], v[168:171], v[208:211], v[76:79]
	v_mfma_f32_16x16x32_bf16 v[116:119], v[168:171], v[184:187], v[116:119]
	v_mfma_f32_16x16x32_bf16 v[116:119], v[164:167], v[180:183], v[116:119]
	v_mfma_f32_16x16x32_bf16 v[112:115], v[172:175], v[180:183], v[112:115]
	v_mfma_f32_16x16x32_bf16 v[112:115], v[176:179], v[184:187], v[112:115]
	v_mfma_f32_16x16x32_bf16 v[96:99], v[176:179], v[192:195], v[96:99]
	v_mfma_f32_16x16x32_bf16 v[96:99], v[172:175], v[188:191], v[96:99]
	v_mfma_f32_16x16x32_bf16 v[100:103], v[164:167], v[188:191], v[100:103]
	v_mfma_f32_16x16x32_bf16 v[100:103], v[168:171], v[192:195], v[100:103]
	v_mfma_f32_16x16x32_bf16 v[84:87], v[168:171], v[200:203], v[84:87]
	v_mfma_f32_16x16x32_bf16 v[84:87], v[164:167], v[196:199], v[84:87]
	v_mfma_f32_16x16x32_bf16 v[80:83], v[172:175], v[196:199], v[80:83]
	v_mfma_f32_16x16x32_bf16 v[80:83], v[176:179], v[200:203], v[80:83]
	v_mfma_f32_16x16x32_bf16 v[72:75], v[176:179], v[208:211], v[72:75]
	v_mfma_f32_16x16x32_bf16 v[72:75], v[172:175], v[204:207], v[72:75]
	s_setprio 0
	s_barrier
	s_add_u32 s28, s26, 0x8000
	s_addc_u32 s29, s27, 0
	s_add_i32 s68, s68, s34
	s_mov_b32 m0, s68
	ds_read_b128 v[180:183], v150 offset:49152
	ds_read_b128 v[184:187], v150 offset:50176
	ds_read_b128 v[188:191], v150 offset:51200
	ds_read_b128 v[192:195], v150 offset:52224
	ds_read_b128 v[196:199], v150 offset:53248
	ds_read_b128 v[200:203], v150 offset:54272
	ds_read_b128 v[204:207], v150 offset:55296
	ds_read_b128 v[208:211], v150 offset:56320
	global_load_lds_dwordx4 v138, s[28:29]
	s_add_i32 m0, s68, 0x2000
	s_add_u32 s26, s26, 0xc000
	s_addc_u32 s27, s27, 0
	global_load_lds_dwordx4 v142, s[28:29]
	s_add_i32 s28, s69, s34
	s_mov_b32 m0, s28
	s_nop 0
	global_load_lds_dwordx4 v138, s[26:27]
	s_add_i32 m0, s28, 0x2000
	s_nop 0
	global_load_lds_dwordx4 v142, s[26:27]
	s_mov_b32 m0, s64
	s_nop 0
	global_load_lds_dwordx4 v136, s[24:25]
	s_mov_b32 m0, s65
	s_nop 0
	global_load_lds_dwordx4 v140, s[24:25]
	s_waitcnt vmcnt(8)
	s_waitcnt lgkmcnt(0)
	v_mfma_f32_16x16x32_bf16 v[68:71], v[52:55], v[180:183], v[68:71]
	v_mfma_f32_16x16x32_bf16 v[68:71], v[152:155], v[184:187], v[68:71]
	v_mfma_f32_16x16x32_bf16 v[64:67], v[160:163], v[184:187], v[64:67]
	v_mfma_f32_16x16x32_bf16 v[64:67], v[156:159], v[180:183], v[64:67]
	s_barrier
	s_setprio 1
	v_mfma_f32_16x16x32_bf16 v[56:59], v[156:159], v[188:191], v[56:59]
	v_mfma_f32_16x16x32_bf16 v[56:59], v[160:163], v[192:195], v[56:59]
	v_mfma_f32_16x16x32_bf16 v[60:63], v[152:155], v[192:195], v[60:63]
	v_mfma_f32_16x16x32_bf16 v[60:63], v[52:55], v[188:191], v[60:63]
	v_mfma_f32_16x16x32_bf16 v[44:47], v[52:55], v[196:199], v[44:47]
	v_mfma_f32_16x16x32_bf16 v[44:47], v[152:155], v[200:203], v[44:47]
	v_mfma_f32_16x16x32_bf16 v[40:43], v[160:163], v[200:203], v[40:43]
	v_mfma_f32_16x16x32_bf16 v[40:43], v[156:159], v[196:199], v[40:43]
	v_mfma_f32_16x16x32_bf16 v[20:23], v[156:159], v[204:207], v[20:23]
	v_mfma_f32_16x16x32_bf16 v[20:23], v[160:163], v[208:211], v[20:23]
	v_mfma_f32_16x16x32_bf16 v[24:27], v[152:155], v[208:211], v[24:27]
	v_mfma_f32_16x16x32_bf16 v[24:27], v[52:55], v[204:207], v[24:27]
	v_mfma_f32_16x16x32_bf16 v[36:39], v[164:167], v[180:183], v[36:39]
	v_mfma_f32_16x16x32_bf16 v[52:55], v[168:171], v[184:187], v[36:39]
	v_mfma_f32_16x16x32_bf16 v[36:39], v[172:175], v[180:183], v[48:51]
	v_mfma_f32_16x16x32_bf16 v[32:35], v[164:167], v[188:191], v[32:35]
	v_mfma_f32_16x16x32_bf16 v[28:31], v[172:175], v[188:191], v[28:31]
	v_mfma_f32_16x16x32_bf16 v[16:19], v[164:167], v[196:199], v[16:19]
	v_mfma_f32_16x16x32_bf16 v[12:15], v[172:175], v[196:199], v[12:15]
	v_mfma_f32_16x16x32_bf16 v[8:11], v[164:167], v[204:207], v[8:11]
	v_mfma_f32_16x16x32_bf16 v[4:7], v[172:175], v[204:207], v[4:7]
	v_mfma_f32_16x16x32_bf16 v[48:51], v[176:179], v[184:187], v[36:39]
	v_mfma_f32_16x16x32_bf16 v[32:35], v[168:171], v[192:195], v[32:35]
	v_mfma_f32_16x16x32_bf16 v[28:31], v[176:179], v[192:195], v[28:31]
	v_mfma_f32_16x16x32_bf16 v[16:19], v[168:171], v[200:203], v[16:19]
	v_mfma_f32_16x16x32_bf16 v[12:15], v[176:179], v[200:203], v[12:15]
	v_mfma_f32_16x16x32_bf16 v[8:11], v[168:171], v[208:211], v[8:11]
	v_mfma_f32_16x16x32_bf16 v[4:7], v[176:179], v[208:211], v[4:7]
	s_setprio 0
	s_barrier
	s_add_i32 s13, s13, 2
	s_add_u32 s22, s22, 0x10000
	s_addc_u32 s23, s23, 0
	s_add_u32 s82, s82, 0x10000
	s_addc_u32 vcc_lo, vcc_lo, 0
	s_cmp_gt_u32 s13, 29
